# prompt attention: K/V tile prefetch distance 2 (second register staging set in the mask registers) on top of the pipelined full-tile path
# baseline (speedup 1.0000x reference)
.LBB0_1551:
	s_and_b32 s38, s36, 7
	s_ashr_i32 s0, s36, 6
	s_ashr_i32 s1, s0, 31
	s_lshl_b32 s6, s38, 8
	s_bfe_u32 s37, s36, 0x30003
	s_lshl_b64 s[20:21], s[0:1], 12
	s_add_i32 s13, s25, s6
	s_add_u32 s22, s20, s13
	s_addc_u32 s23, s21, 0
	v_mov_b32_e32 v17, s23
	v_or_b32_e32 v16, s22, v124
	v_mov_b64_e32 v[18:19], s[8:9]
	v_mad_u64_u32 v[18:19], s[16:17], v16, s31, v[18:19]
	s_mul_i32 s39, s37, 0x60
	v_lshlrev_b64 v[16:17], 6, v[16:17]
	v_mad_i32_i24 v19, s23, v209, v19
	s_lshl_b32 s6, s39, 1
	v_lshl_add_u64 v[16:17], s[10:11], 0, v[16:17]
	s_lshl_b32 s16, s37, 2
	s_mov_b32 s17, s7
	v_lshl_add_u64 v[18:19], v[18:19], 0, s[6:7]
	v_lshl_add_u64 v[16:17], v[16:17], 0, s[16:17]
	v_lshl_add_u64 v[36:37], v[128:129], 1, v[18:19]
	global_load_dword v78, v[16:17], off
	global_load_dword v79, v[16:17], off offset:32
	global_load_dwordx4 v[24:27], v[36:37], off
	global_load_dwordx4 v[20:23], v[36:37], off offset:32
	global_load_dwordx4 v[32:35], v[130:131], off
	global_load_dwordx4 v[28:31], v[130:131], off offset:16
	global_load_dwordx4 v[38:41], v[130:131], off offset:64
	global_load_dwordx4 v[42:45], v[130:131], off offset:80
	global_load_dwordx4 v[16:19], v[36:37], off offset:160
	s_mul_i32 s17, s0, 0x600000
	s_lshl_b32 s41, s38, 1
	s_mul_hi_i32 s16, s0, 0x600000
	s_add_u32 s17, s26, s17
	s_addc_u32 s18, s27, s16
	s_add_u32 s16, s17, s6
	s_addc_u32 s17, s18, 0
	s_lshl_b64 s[0:1], s[0:1], 22
	s_lshl_b32 s40, s37, 6
	s_add_u32 s0, s14, s0
	s_addc_u32 s1, s24, s1
	s_lshl_b32 s6, s37, 7
	s_add_u32 s18, s0, s6
	s_addc_u32 s19, s1, 0
	global_load_dwordx4 v[46:49], v[130:131], off offset:144
	global_load_dwordx4 v[50:53], v[130:131], off offset:128
	global_load_dwordx4 v[54:57], v[130:131], off offset:208
	global_load_dwordx4 v[58:61], v[130:131], off offset:192
	global_load_dwordx4 v[62:65], v[130:131], off offset:272
	global_load_dwordx4 v[66:69], v[130:131], off offset:256
	global_load_dwordx4 v[70:73], v[36:37], off offset:64
	global_load_dwordx4 v[74:77], v[36:37], off offset:96
	global_load_dwordx4 v[100:103], v[36:37], off offset:128
	v_lshl_add_u64 v[176:177], v[140:141], 1, s[18:19]
	global_load_dwordx4 v[80:83], v[176:177], off
	v_lshl_add_u64 v[178:179], v[132:133], 1, s[16:17]
	v_lshl_add_u64 v[182:183], v[136:137], 1, s[16:17]
	v_lshl_add_u64 v[180:181], v[134:135], 1, s[16:17]
	v_lshl_add_u64 v[184:185], v[138:139], 1, s[18:19]
	v_or_b32_e32 v210, s13, v124
	s_mov_b32 s12, 0
	s_add_i32 s41, s41, 2
	s_or_b32 s42, s13, 31
	s_lshl_b32 s43, s38, 2
	v_subrev_u32_e32 v211, 32, v210
	v_subrev_u32_e32 v212, 33, v210
	v_subrev_u32_e32 v213, 34, v210
	v_subrev_u32_e32 v214, 35, v210
	v_add_u32_e32 v215, -8, v210
	v_subrev_u32_e32 v216, 40, v210
	v_add_u32_e32 v217, -9, v210
	v_subrev_u32_e32 v218, 41, v210
	v_add_u32_e32 v219, -10, v210
	v_subrev_u32_e32 v220, 42, v210
	v_add_u32_e32 v221, -11, v210
	v_subrev_u32_e32 v222, 43, v210
	v_add_u32_e32 v223, -16, v210
	v_subrev_u32_e32 v224, 48, v210
	v_subrev_u32_e32 v225, 17, v210
	v_subrev_u32_e32 v226, 49, v210
	v_subrev_u32_e32 v227, 18, v210
	v_subrev_u32_e32 v228, 50, v210
	v_subrev_u32_e32 v229, 19, v210
	v_subrev_u32_e32 v230, 51, v210
	v_subrev_u32_e32 v231, 24, v210
	v_subrev_u32_e32 v232, 56, v210
	v_subrev_u32_e32 v233, 25, v210
	v_subrev_u32_e32 v234, 57, v210
	v_subrev_u32_e32 v235, 26, v210
	v_subrev_u32_e32 v236, 58, v210
	v_subrev_u32_e32 v237, 27, v210
	v_subrev_u32_e32 v238, 59, v210
	v_mov_b32_e32 v239, 0
	s_waitcnt vmcnt(17)
	v_add_f32_e32 v84, v78, v79
	v_fmamk_f32 v84, v84, 0x3c2aaaab, v143
	v_mul_f32_e32 v85, 0x4f800000, v84
	v_cmp_gt_f32_e32 vcc, s34, v84
	s_waitcnt vmcnt(16)
	v_lshlrev_b32_e32 v36, 16, v24
	v_and_b32_e32 v37, 0xffff0000, v24
	v_cndmask_b32_e32 v86, v84, v85, vcc
	v_sqrt_f32_e32 v87, v86
	s_waitcnt vmcnt(15)
	v_lshlrev_b32_e32 v84, 16, v20
	v_and_b32_e32 v85, 0xffff0000, v20
	v_lshlrev_b32_e32 v24, 16, v25
	v_add_u32_e32 v20, -1, v87
	v_add_u32_e32 v88, 1, v87
	v_fma_f32 v89, -v20, v87, v86
	v_fma_f32 v90, -v88, v87, v86
	v_cmp_ge_f32_e64 s[0:1], 0, v89
	v_and_b32_e32 v25, 0xffff0000, v25
	v_lshlrev_b32_e32 v78, 16, v26
	v_cndmask_b32_e64 v20, v87, v20, s[0:1]
	v_cmp_lt_f32_e64 s[0:1], 0, v90
	v_and_b32_e32 v79, 0xffff0000, v26
	v_lshlrev_b32_e32 v26, 16, v27
	v_cndmask_b32_e64 v20, v20, v88, s[0:1]
	v_mul_f32_e32 v87, 0x37800000, v20
	v_cndmask_b32_e32 v20, v20, v87, vcc
	v_cmp_class_f32_e32 vcc, v86, v208
	v_and_b32_e32 v27, 0xffff0000, v27
	s_nop 0
	v_cndmask_b32_e32 v86, v20, v86, vcc
	v_div_scale_f32 v87, s[0:1], v86, v86, 1.0
	v_rcp_f32_e32 v88, v87
	v_div_scale_f32 v89, vcc, 1.0, v86, 1.0
	v_lshlrev_b32_e32 v20, 16, v21
	v_fma_f32 v90, -v87, v88, 1.0
	v_fmac_f32_e32 v88, v90, v88
	v_mul_f32_e32 v90, v89, v88
	v_fma_f32 v91, -v87, v90, v89
	v_fmac_f32_e32 v90, v91, v88
	v_fma_f32 v87, -v87, v90, v89
	v_div_fmas_f32 v87, v87, v88, v90
	v_div_fixup_f32 v112, v87, v86, 1.0
	s_waitcnt vmcnt(14)
	v_pk_mul_f32 v[34:35], v[34:35], v[112:113] op_sel_hi:[1,0]
	s_waitcnt vmcnt(13)
	v_pk_mul_f32 v[30:31], v[30:31], v[112:113] op_sel_hi:[1,0]
	v_pk_mul_f32 v[28:29], v[28:29], v[112:113] op_sel_hi:[1,0]
	s_waitcnt vmcnt(12)
	v_pk_mul_f32 v[38:39], v[38:39], v[112:113] op_sel_hi:[1,0]
	v_pk_mul_f32 v[24:25], v[34:35], v[24:25]
	v_pk_mul_f32 v[28:29], v[28:29], v[78:79]
	v_pk_mul_f32 v[26:27], v[30:31], v[26:27]
	v_pk_mul_f32 v[30:31], v[38:39], v[84:85]
	v_cvt_pk_bf16_f32 v85, v24, v25
	v_cvt_pk_bf16_f32 v86, v28, v29
	v_cvt_pk_bf16_f32 v87, v26, v27
	v_cvt_pk_bf16_f32 v88, v30, v31
	global_load_dwordx4 v[24:27], v[130:131], off offset:336
	global_load_dwordx4 v[28:31], v[130:131], off offset:320
	global_load_dwordx4 v[104:107], v[178:179], off
	global_load_dwordx4 v[108:111], v[180:181], off
	global_load_dwordx4 v[116:119], v[182:183], off
	global_load_dwordx4 v[120:123], v[184:185], off
	v_pk_mul_f32 v[40:41], v[40:41], v[112:113] op_sel_hi:[1,0]
	v_and_b32_e32 v21, 0xffff0000, v21
	v_pk_mul_f32 v[20:21], v[40:41], v[20:21]
	s_waitcnt vmcnt(17)
	v_pk_mul_f32 v[42:43], v[42:43], v[112:113] op_sel_hi:[1,0]
	v_cvt_pk_bf16_f32 v89, v20, v21
	v_lshlrev_b32_e32 v20, 16, v22
	v_and_b32_e32 v21, 0xffff0000, v22
	v_pk_mul_f32 v[32:33], v[32:33], v[112:113] op_sel_hi:[1,0]
	v_pk_mul_f32 v[20:21], v[42:43], v[20:21]
	v_pk_mul_f32 v[44:45], v[44:45], v[112:113] op_sel_hi:[1,0]
	v_pk_mul_f32 v[32:33], v[32:33], v[36:37]
	v_cvt_pk_bf16_f32 v90, v20, v21
	v_lshlrev_b32_e32 v20, 16, v23
	v_and_b32_e32 v21, 0xffff0000, v23
	s_waitcnt vmcnt(14)
	v_pk_mul_f32 v[22:23], v[50:51], v[112:113] op_sel_hi:[1,0]
	s_waitcnt vmcnt(9)
	v_lshlrev_b32_e32 v36, 16, v70
	v_and_b32_e32 v37, 0xffff0000, v70
	v_pk_mul_f32 v[20:21], v[44:45], v[20:21]
	v_pk_mul_f32 v[22:23], v[22:23], v[36:37]
	v_cvt_pk_bf16_f32 v91, v20, v21
	v_pk_mul_f32 v[20:21], v[52:53], v[112:113] op_sel_hi:[1,0]
	v_cvt_pk_bf16_f32 v92, v22, v23
	v_lshlrev_b32_e32 v22, 16, v71
	v_and_b32_e32 v23, 0xffff0000, v71
	v_pk_mul_f32 v[20:21], v[20:21], v[22:23]
	v_pk_mul_f32 v[34:35], v[46:47], v[112:113] op_sel_hi:[1,0]
	v_cvt_pk_bf16_f32 v93, v20, v21
	v_lshlrev_b32_e32 v20, 16, v72
	v_and_b32_e32 v21, 0xffff0000, v72
	v_pk_mul_f32 v[20:21], v[34:35], v[20:21]
	v_cvt_pk_bf16_f32 v84, v32, v33
	v_pk_mul_f32 v[32:33], v[48:49], v[112:113] op_sel_hi:[1,0]
	v_cvt_pk_bf16_f32 v94, v20, v21
	v_lshlrev_b32_e32 v20, 16, v73
	v_and_b32_e32 v21, 0xffff0000, v73
	v_pk_mul_f32 v[22:23], v[112:113], v[58:59] op_sel_hi:[0,1]
	s_waitcnt vmcnt(8)
	v_lshlrev_b32_e32 v36, 16, v74
	v_and_b32_e32 v37, 0xffff0000, v74
	v_pk_mul_f32 v[20:21], v[32:33], v[20:21]
	v_pk_mul_f32 v[22:23], v[22:23], v[36:37]
	v_cvt_pk_bf16_f32 v95, v20, v21
	v_pk_mul_f32 v[20:21], v[112:113], v[60:61] op_sel_hi:[0,1]
	v_cvt_pk_bf16_f32 v96, v22, v23
	v_lshlrev_b32_e32 v22, 16, v75
	v_and_b32_e32 v23, 0xffff0000, v75
	v_pk_mul_f32 v[20:21], v[20:21], v[22:23]
	v_pk_mul_f32 v[34:35], v[112:113], v[54:55] op_sel_hi:[0,1]
	v_cvt_pk_bf16_f32 v97, v20, v21
	v_lshlrev_b32_e32 v20, 16, v76
	v_and_b32_e32 v21, 0xffff0000, v76
	v_pk_mul_f32 v[20:21], v[34:35], v[20:21]
	v_pk_mul_f32 v[32:33], v[112:113], v[56:57] op_sel_hi:[0,1]
	v_cvt_pk_bf16_f32 v98, v20, v21
	v_lshlrev_b32_e32 v20, 16, v77
	v_and_b32_e32 v21, 0xffff0000, v77
	v_pk_mul_f32 v[22:23], v[112:113], v[66:67] op_sel_hi:[0,1]
	s_waitcnt vmcnt(7)
	v_lshlrev_b32_e32 v36, 16, v100
	v_and_b32_e32 v37, 0xffff0000, v100
	v_pk_mul_f32 v[20:21], v[32:33], v[20:21]
	v_pk_mul_f32 v[22:23], v[22:23], v[36:37]
	v_cvt_pk_bf16_f32 v99, v20, v21
	v_pk_mul_f32 v[20:21], v[112:113], v[68:69] op_sel_hi:[0,1]
	v_cvt_pk_bf16_f32 v100, v22, v23
	v_lshlrev_b32_e32 v22, 16, v101
	v_and_b32_e32 v23, 0xffff0000, v101
	v_pk_mul_f32 v[20:21], v[20:21], v[22:23]
	v_pk_mul_f32 v[34:35], v[112:113], v[62:63] op_sel_hi:[0,1]
	v_cvt_pk_bf16_f32 v101, v20, v21
	v_lshlrev_b32_e32 v20, 16, v102
	v_and_b32_e32 v21, 0xffff0000, v102
	v_pk_mul_f32 v[20:21], v[34:35], v[20:21]
	v_pk_mul_f32 v[32:33], v[112:113], v[64:65] op_sel_hi:[0,1]
	v_cvt_pk_bf16_f32 v102, v20, v21
	v_lshlrev_b32_e32 v20, 16, v103
	v_and_b32_e32 v21, 0xffff0000, v103
	v_pk_mul_f32 v[20:21], v[32:33], v[20:21]
	s_waitcnt vmcnt(5)
	v_pk_mul_f32 v[26:27], v[112:113], v[26:27] op_sel_hi:[0,1]
	v_cvt_pk_bf16_f32 v103, v20, v21
	s_waitcnt vmcnt(4)
	v_pk_mul_f32 v[20:21], v[112:113], v[30:31] op_sel_hi:[0,1]
	v_pk_mul_f32 v[22:23], v[112:113], v[28:29] op_sel_hi:[0,1]
	v_lshlrev_b32_e32 v28, 16, v16
	v_and_b32_e32 v29, 0xffff0000, v16
	v_lshlrev_b32_e32 v16, 16, v17
	v_and_b32_e32 v17, 0xffff0000, v17
	v_pk_mul_f32 v[16:17], v[20:21], v[16:17]
	v_pk_mul_f32 v[24:25], v[112:113], v[24:25] op_sel_hi:[0,1]
	v_cvt_pk_bf16_f32 v113, v16, v17
	v_lshlrev_b32_e32 v16, 16, v18
	v_and_b32_e32 v17, 0xffff0000, v18
	v_pk_mul_f32 v[16:17], v[24:25], v[16:17]
	v_pk_mul_f32 v[22:23], v[22:23], v[28:29]
	v_cvt_pk_bf16_f32 v114, v16, v17
	v_lshlrev_b32_e32 v16, 16, v19
	v_and_b32_e32 v17, 0xffff0000, v19
	v_pk_mul_f32 v[16:17], v[26:27], v[16:17]
	v_mov_b32_e32 v30, v127
	v_mov_b32_e32 v31, v127
	v_cvt_pk_bf16_f32 v112, v22, v23
	v_cvt_pk_bf16_f32 v115, v16, v17
	v_mov_b32_e32 v16, v127
	v_mov_b32_e32 v17, v127
	v_mov_b32_e32 v18, v127
	v_mov_b32_e32 v19, v127
	v_mov_b32_e32 v20, v127
	v_mov_b32_e32 v21, v127
	v_mov_b32_e32 v22, v127
	v_mov_b32_e32 v23, v127
	v_mov_b32_e32 v24, v127
	v_mov_b32_e32 v25, v127
	v_mov_b32_e32 v26, v127
	v_mov_b32_e32 v27, v127
	v_mov_b32_e32 v28, v127
	v_mov_b32_e32 v29, v127
	v_mov_b64_e32 v[46:47], v[30:31]
	v_mov_b64_e32 v[44:45], v[28:29]
	v_mov_b64_e32 v[42:43], v[26:27]
	v_mov_b64_e32 v[40:41], v[24:25]
	v_mov_b64_e32 v[38:39], v[22:23]
	v_mov_b64_e32 v[36:37], v[20:21]
	v_mov_b64_e32 v[34:35], v[18:19]
	v_mov_b64_e32 v[32:33], v[16:17]
	s_cmp_lt_u32 s41, 4
	s_cbranch_scc1 .Lmy_pa1_skip
	s_add_u32 s44, s16, 0x30000
	s_addc_u32 s45, s17, 0
	s_add_u32 s46, s18, 0x20000
	s_addc_u32 s47, s19, 0
	v_lshl_add_u64 v[48:49], v[132:133], 1, s[44:45]
	v_lshl_add_u64 v[50:51], v[134:135], 1, s[44:45]
	v_lshl_add_u64 v[52:53], v[136:137], 1, s[44:45]
	v_lshl_add_u64 v[54:55], v[138:139], 1, s[46:47]
	v_lshl_add_u64 v[56:57], v[140:141], 1, s[46:47]
	global_load_dwordx4 v[212:215], v[48:49], off
	global_load_dwordx4 v[216:219], v[50:51], off
	global_load_dwordx4 v[220:223], v[52:53], off
	global_load_dwordx4 v[224:227], v[54:55], off
	global_load_dwordx4 v[228:231], v[56:57], off
	v_add_u32_e32 v240, 0x6800, v203
	v_add_u32_e32 v241, 0x4800, v204
	s_mov_b32 s12, 0
.Lmy_pa1_pair:
	v_add_u32_e32 v48, v125, v190
	v_add_u32_e32 v49, v191, v192
	v_add_u32_e32 v50, v193, v200
	v_add_u32_e32 v51, v205, v201
	v_add_u32_e32 v52, v205, v202
	s_waitcnt vmcnt(5)
	ds_write_b128 v48, v[104:107]
	ds_write_b128 v49, v[108:111]
	ds_write_b128 v50, v[116:119]
	ds_write_b128 v51, v[120:123] offset:53248
	ds_write_b128 v52, v[80:83] offset:53248
	s_waitcnt lgkmcnt(0)
	s_barrier
	s_add_i32 s13, s12, 2
	s_mul_i32 s44, s13, 0x30000
	s_lshl_b32 s46, s13, 17
	s_add_u32 s44, s16, s44
	s_addc_u32 s45, s17, 0
	s_add_u32 s46, s18, s46
	s_addc_u32 s47, s19, 0
	v_lshl_add_u64 v[48:49], v[132:133], 1, s[44:45]
	v_lshl_add_u64 v[50:51], v[134:135], 1, s[44:45]
	v_lshl_add_u64 v[52:53], v[136:137], 1, s[44:45]
	v_lshl_add_u64 v[54:55], v[138:139], 1, s[46:47]
	v_lshl_add_u64 v[56:57], v[140:141], 1, s[46:47]
	global_load_dwordx4 v[104:107], v[48:49], off
	global_load_dwordx4 v[108:111], v[50:51], off
	global_load_dwordx4 v[116:119], v[52:53], off
	global_load_dwordx4 v[120:123], v[54:55], off
	global_load_dwordx4 v[80:83], v[56:57], off
	v_mad_u32_u24 v184, v124, s28, v203
	v_add_u32_e32 v185, 0x2400, v204
	ds_read_b128 v[186:189], v184
	ds_read_b128 v[242:245], v184 offset:6656
	ds_read_b128 v[246:249], v184 offset:32
	ds_read_b128 v[250:253], v184 offset:6688
	ds_read_b128 v[176:179], v184 offset:64
	ds_read_b128 v[180:183], v184 offset:6720
	s_waitcnt lgkmcnt(5)
	v_mfma_f32_32x32x16_bf16 v[48:63], v[186:189], v[84:87], v[0:15]
	ds_read_b128 v[186:189], v184 offset:96
	s_waitcnt lgkmcnt(5)
	v_mfma_f32_32x32x16_bf16 v[64:79], v[242:245], v[84:87], v[0:15]
	ds_read_b128 v[242:245], v184 offset:6752
	s_waitcnt lgkmcnt(5)
	v_mfma_f32_32x32x16_bf16 v[48:63], v[246:249], v[88:91], v[48:63]
	ds_read_b128 v[246:249], v184 offset:128
	s_waitcnt lgkmcnt(5)
	v_mfma_f32_32x32x16_bf16 v[64:79], v[250:253], v[88:91], v[64:79]
	ds_read_b128 v[250:253], v184 offset:6784
	s_waitcnt lgkmcnt(5)
	v_mfma_f32_32x32x16_bf16 v[48:63], v[176:179], v[92:95], v[48:63]
	ds_read_b128 v[176:179], v184 offset:160
	s_waitcnt lgkmcnt(5)
	v_mfma_f32_32x32x16_bf16 v[64:79], v[180:183], v[92:95], v[64:79]
	ds_read_b128 v[180:183], v184 offset:6816
	s_waitcnt lgkmcnt(5)
	v_mfma_f32_32x32x16_bf16 v[48:63], v[186:189], v[96:99], v[48:63]
	ds_read_b128 v[186:189], v184 offset:13312
	s_waitcnt lgkmcnt(5)
	v_mfma_f32_32x32x16_bf16 v[64:79], v[242:245], v[96:99], v[64:79]
	ds_read_b128 v[242:245], v184 offset:19968
	s_waitcnt lgkmcnt(5)
	v_mfma_f32_32x32x16_bf16 v[48:63], v[246:249], v[100:103], v[48:63]
	ds_read_b128 v[246:249], v184 offset:13344
	s_waitcnt lgkmcnt(5)
	v_mfma_f32_32x32x16_bf16 v[64:79], v[250:253], v[100:103], v[64:79]
	ds_read_b128 v[250:253], v184 offset:20000
	s_waitcnt lgkmcnt(5)
	v_mfma_f32_32x32x16_bf16 v[48:63], v[176:179], v[112:115], v[48:63]
	ds_read_b128 v[176:179], v184 offset:13376
	s_waitcnt lgkmcnt(5)
	v_mfma_f32_32x32x16_bf16 v[64:79], v[180:183], v[112:115], v[64:79]
	ds_read_b128 v[180:183], v184 offset:20032
	s_waitcnt lgkmcnt(5)
	v_mfma_f32_32x32x16_bf16 v[144:159], v[186:189], v[84:87], v[0:15]
	ds_read_b128 v[186:189], v184 offset:13408
	s_waitcnt lgkmcnt(5)
	v_mfma_f32_32x32x16_bf16 v[160:175], v[242:245], v[84:87], v[0:15]
	ds_read_b128 v[242:245], v184 offset:20064
	s_nop 4
	v_exp_f32_e32 v48, v48
	v_exp_f32_e32 v49, v49
	v_exp_f32_e32 v50, v50
	s_waitcnt lgkmcnt(5)
	v_mfma_f32_32x32x16_bf16 v[144:159], v[246:249], v[88:91], v[144:159]
	ds_read_b128 v[246:249], v184 offset:13440
	v_exp_f32_e32 v51, v51
	v_exp_f32_e32 v52, v52
	v_exp_f32_e32 v53, v53
	s_waitcnt lgkmcnt(5)
	v_mfma_f32_32x32x16_bf16 v[160:175], v[250:253], v[88:91], v[160:175]
	ds_read_b128 v[250:253], v184 offset:20096
	v_exp_f32_e32 v54, v54
	v_exp_f32_e32 v55, v55
	v_exp_f32_e32 v56, v56
	s_waitcnt lgkmcnt(5)
	v_mfma_f32_32x32x16_bf16 v[144:159], v[176:179], v[92:95], v[144:159]
	ds_read_b128 v[176:179], v184 offset:13472
	v_exp_f32_e32 v57, v57
	v_exp_f32_e32 v58, v58
	v_exp_f32_e32 v59, v59
	s_waitcnt lgkmcnt(5)
	v_mfma_f32_32x32x16_bf16 v[160:175], v[180:183], v[92:95], v[160:175]
	ds_read_b128 v[180:183], v184 offset:20128
	v_exp_f32_e32 v60, v60
	v_exp_f32_e32 v61, v61
	v_exp_f32_e32 v62, v62
	s_waitcnt lgkmcnt(5)
	v_mfma_f32_32x32x16_bf16 v[144:159], v[186:189], v[96:99], v[144:159]
	ds_read_b64_tr_b16 v[186:187], v204 offset:53248
	ds_read_b64_tr_b16 v[188:189], v204 offset:54400
	v_exp_f32_e32 v63, v63
	v_exp_f32_e32 v64, v64
	v_exp_f32_e32 v65, v65
	s_waitcnt lgkmcnt(6)
	v_mfma_f32_32x32x16_bf16 v[160:175], v[242:245], v[96:99], v[160:175]
	ds_read_b64_tr_b16 v[242:243], v204 offset:53312
	ds_read_b64_tr_b16 v[244:245], v204 offset:54464
	v_exp_f32_e32 v66, v66
	v_exp_f32_e32 v67, v67
	v_exp_f32_e32 v68, v68
	s_waitcnt lgkmcnt(7)
	v_mfma_f32_32x32x16_bf16 v[144:159], v[246:249], v[100:103], v[144:159]
	ds_read_b64_tr_b16 v[246:247], v204 offset:55552
	ds_read_b64_tr_b16 v[248:249], v204 offset:56704
	v_exp_f32_e32 v69, v69
	v_exp_f32_e32 v70, v70
	v_exp_f32_e32 v71, v71
	s_waitcnt lgkmcnt(8)
	v_mfma_f32_32x32x16_bf16 v[160:175], v[250:253], v[100:103], v[160:175]
	ds_read_b64_tr_b16 v[250:251], v204 offset:55616
	ds_read_b64_tr_b16 v[252:253], v204 offset:56768
	v_exp_f32_e32 v72, v72
	v_exp_f32_e32 v73, v73
	v_exp_f32_e32 v74, v74
	s_waitcnt lgkmcnt(9)
	v_mfma_f32_32x32x16_bf16 v[144:159], v[176:179], v[112:115], v[144:159]
	v_cvt_pk_bf16_f32 v176, v48, v49
	v_cvt_pk_bf16_f32 v177, v50, v51
	v_cvt_pk_bf16_f32 v178, v52, v53
	v_cvt_pk_bf16_f32 v179, v54, v55
	v_exp_f32_e32 v75, v75
	s_waitcnt lgkmcnt(8)
	v_mfma_f32_32x32x16_bf16 v[160:175], v[180:183], v[112:115], v[160:175]
	v_exp_f32_e32 v76, v76
	v_exp_f32_e32 v77, v77
	v_exp_f32_e32 v78, v78
	s_waitcnt lgkmcnt(6)
	v_mfma_f32_32x32x16_bf16 v[16:31], v[176:179], v[186:189], v[16:31]
	ds_read_b64_tr_b16 v[186:187], v204 offset:57856
	ds_read_b64_tr_b16 v[188:189], v204 offset:59008
	v_cvt_pk_bf16_f32 v180, v56, v57
	v_cvt_pk_bf16_f32 v181, v58, v59
	v_cvt_pk_bf16_f32 v182, v60, v61
	v_cvt_pk_bf16_f32 v183, v62, v63
	v_exp_f32_e32 v79, v79
	v_exp_f32_e32 v144, v144
	s_waitcnt lgkmcnt(6)
	v_mfma_f32_32x32x16_bf16 v[32:47], v[176:179], v[242:245], v[32:47]
	ds_read_b64_tr_b16 v[242:243], v204 offset:57920
	ds_read_b64_tr_b16 v[244:245], v204 offset:59072
	v_cvt_pk_bf16_f32 v176, v64, v65
	v_cvt_pk_bf16_f32 v177, v66, v67
	v_cvt_pk_bf16_f32 v178, v68, v69
	v_cvt_pk_bf16_f32 v179, v70, v71
	v_exp_f32_e32 v145, v145
	v_exp_f32_e32 v146, v146
	s_waitcnt lgkmcnt(6)
	v_mfma_f32_32x32x16_bf16 v[16:31], v[180:183], v[246:249], v[16:31]
	ds_read_b64_tr_b16 v[246:247], v204 offset:60160
	ds_read_b64_tr_b16 v[248:249], v204 offset:61312
	v_exp_f32_e32 v147, v147
	v_exp_f32_e32 v148, v148
	v_exp_f32_e32 v149, v149
	v_exp_f32_e32 v150, v150
	s_waitcnt lgkmcnt(6)
	v_mfma_f32_32x32x16_bf16 v[32:47], v[180:183], v[250:253], v[32:47]
	ds_read_b64_tr_b16 v[250:251], v204 offset:60224
	ds_read_b64_tr_b16 v[252:253], v204 offset:61376
	v_cvt_pk_bf16_f32 v180, v72, v73
	v_cvt_pk_bf16_f32 v181, v74, v75
	v_cvt_pk_bf16_f32 v182, v76, v77
	v_cvt_pk_bf16_f32 v183, v78, v79
	v_exp_f32_e32 v151, v151
	v_exp_f32_e32 v152, v152
	s_waitcnt lgkmcnt(6)
	v_mfma_f32_32x32x16_bf16 v[16:31], v[176:179], v[186:189], v[16:31]
	ds_read_b64_tr_b16 v[186:187], v185 offset:53248
	ds_read_b64_tr_b16 v[188:189], v185 offset:54400
	v_exp_f32_e32 v153, v153
	v_exp_f32_e32 v154, v154
	v_exp_f32_e32 v155, v155
	v_exp_f32_e32 v156, v156
	s_waitcnt lgkmcnt(6)
	v_mfma_f32_32x32x16_bf16 v[32:47], v[176:179], v[242:245], v[32:47]
	ds_read_b64_tr_b16 v[242:243], v185 offset:53312
	ds_read_b64_tr_b16 v[244:245], v185 offset:54464
	v_cvt_pk_bf16_f32 v176, v144, v145
	v_cvt_pk_bf16_f32 v177, v146, v147
	v_cvt_pk_bf16_f32 v178, v148, v149
	v_cvt_pk_bf16_f32 v179, v150, v151
	v_exp_f32_e32 v157, v157
	v_exp_f32_e32 v158, v158
	s_waitcnt lgkmcnt(6)
	v_mfma_f32_32x32x16_bf16 v[16:31], v[180:183], v[246:249], v[16:31]
	ds_read_b64_tr_b16 v[246:247], v185 offset:55552
	ds_read_b64_tr_b16 v[248:249], v185 offset:56704
	v_exp_f32_e32 v159, v159
	v_exp_f32_e32 v160, v160
	v_exp_f32_e32 v161, v161
	v_exp_f32_e32 v162, v162
	s_waitcnt lgkmcnt(6)
	v_mfma_f32_32x32x16_bf16 v[32:47], v[180:183], v[250:253], v[32:47]
	ds_read_b64_tr_b16 v[250:251], v185 offset:55616
	ds_read_b64_tr_b16 v[252:253], v185 offset:56768
	v_cvt_pk_bf16_f32 v180, v152, v153
	v_cvt_pk_bf16_f32 v181, v154, v155
	v_cvt_pk_bf16_f32 v182, v156, v157
	v_cvt_pk_bf16_f32 v183, v158, v159
	v_exp_f32_e32 v163, v163
	v_exp_f32_e32 v164, v164
	s_waitcnt lgkmcnt(6)
	v_mfma_f32_32x32x16_bf16 v[16:31], v[176:179], v[186:189], v[16:31]
	ds_read_b64_tr_b16 v[186:187], v185 offset:57856
	ds_read_b64_tr_b16 v[188:189], v185 offset:59008
	v_exp_f32_e32 v165, v165
	v_exp_f32_e32 v166, v166
	v_exp_f32_e32 v167, v167
	v_exp_f32_e32 v168, v168
	s_waitcnt lgkmcnt(6)
	v_mfma_f32_32x32x16_bf16 v[32:47], v[176:179], v[242:245], v[32:47]
	ds_read_b64_tr_b16 v[242:243], v185 offset:57920
	ds_read_b64_tr_b16 v[244:245], v185 offset:59072
	v_cvt_pk_bf16_f32 v176, v160, v161
	v_cvt_pk_bf16_f32 v177, v162, v163
	v_cvt_pk_bf16_f32 v178, v164, v165
	v_cvt_pk_bf16_f32 v179, v166, v167
	v_exp_f32_e32 v169, v169
	v_exp_f32_e32 v170, v170
	s_waitcnt lgkmcnt(6)
	v_mfma_f32_32x32x16_bf16 v[16:31], v[180:183], v[246:249], v[16:31]
	ds_read_b64_tr_b16 v[246:247], v185 offset:60160
	ds_read_b64_tr_b16 v[248:249], v185 offset:61312
	v_exp_f32_e32 v171, v171
	v_exp_f32_e32 v172, v172
	v_exp_f32_e32 v173, v173
	v_exp_f32_e32 v174, v174
	s_waitcnt lgkmcnt(6)
	v_mfma_f32_32x32x16_bf16 v[32:47], v[180:183], v[250:253], v[32:47]
	ds_read_b64_tr_b16 v[250:251], v185 offset:60224
	ds_read_b64_tr_b16 v[252:253], v185 offset:61376
	v_exp_f32_e32 v175, v175
	v_cvt_pk_bf16_f32 v180, v168, v169
	v_cvt_pk_bf16_f32 v181, v170, v171
	v_cvt_pk_bf16_f32 v182, v172, v173
	v_cvt_pk_bf16_f32 v183, v174, v175
	v_add_f32_e32 v184, v48, v64
	v_add_f32_e32 v184, v184, v49
	s_waitcnt lgkmcnt(6)
	v_mfma_f32_32x32x16_bf16 v[16:31], v[176:179], v[186:189], v[16:31]
	v_add_f32_e32 v184, v184, v65
	v_add_f32_e32 v184, v184, v50
	v_add_f32_e32 v184, v184, v66
	v_add_f32_e32 v184, v184, v51
	v_add_f32_e32 v184, v184, v67
	v_add_f32_e32 v184, v184, v52
	v_add_f32_e32 v184, v184, v68
	v_add_f32_e32 v184, v184, v53
	s_waitcnt lgkmcnt(4)
	v_mfma_f32_32x32x16_bf16 v[32:47], v[176:179], v[242:245], v[32:47]
	v_add_f32_e32 v184, v184, v69
	v_add_f32_e32 v184, v184, v54
	v_add_f32_e32 v184, v184, v70
	v_add_f32_e32 v184, v184, v55
	v_add_f32_e32 v184, v184, v71
	v_add_f32_e32 v184, v184, v56
	v_add_f32_e32 v184, v184, v72
	v_add_f32_e32 v184, v184, v57
	s_waitcnt lgkmcnt(2)
	v_mfma_f32_32x32x16_bf16 v[16:31], v[180:183], v[246:249], v[16:31]
	v_add_f32_e32 v184, v184, v73
	v_add_f32_e32 v184, v184, v58
	v_add_f32_e32 v184, v184, v74
	v_add_f32_e32 v184, v184, v59
	v_add_f32_e32 v184, v184, v75
	v_add_f32_e32 v184, v184, v60
	v_add_f32_e32 v184, v184, v76
	v_add_f32_e32 v184, v184, v61
	s_waitcnt lgkmcnt(0)
	v_mfma_f32_32x32x16_bf16 v[32:47], v[180:183], v[250:253], v[32:47]
	v_add_f32_e32 v184, v184, v77
	v_add_f32_e32 v184, v184, v62
	v_add_f32_e32 v184, v184, v78
	v_add_f32_e32 v184, v184, v63
	v_add_f32_e32 v184, v184, v79
	v_add_f32_e32 v184, v184, v144
	v_add_f32_e32 v184, v184, v160
	v_add_f32_e32 v184, v184, v145
	v_add_f32_e32 v184, v184, v161
	v_add_f32_e32 v184, v184, v146
	v_add_f32_e32 v184, v184, v162
	v_add_f32_e32 v184, v184, v147
	v_add_f32_e32 v184, v184, v163
	v_add_f32_e32 v184, v184, v148
	v_add_f32_e32 v184, v184, v164
	v_add_f32_e32 v184, v184, v149
	v_add_f32_e32 v184, v184, v165
	v_add_f32_e32 v184, v184, v150
	v_add_f32_e32 v184, v184, v166
	v_add_f32_e32 v184, v184, v151
	v_add_f32_e32 v184, v184, v167
	v_add_f32_e32 v184, v184, v152
	v_add_f32_e32 v184, v184, v168
	v_add_f32_e32 v184, v184, v153
	v_add_f32_e32 v184, v184, v169
	v_add_f32_e32 v184, v184, v154
	v_add_f32_e32 v184, v184, v170
	v_add_f32_e32 v184, v184, v155
	v_add_f32_e32 v184, v184, v171
	v_add_f32_e32 v184, v184, v156
	v_add_f32_e32 v184, v184, v172
	v_add_f32_e32 v184, v184, v157
	v_add_f32_e32 v184, v184, v173
	v_add_f32_e32 v184, v184, v158
	v_add_f32_e32 v184, v184, v174
	v_add_f32_e32 v184, v184, v159
	v_add_f32_e32 v184, v184, v175
	v_add_f32_e32 v239, v239, v184
	s_movk_i32 s13, 0x6800
	v_add3_u32 v48, s13, v125, v190
	v_add3_u32 v49, s13, v191, v192
	v_add3_u32 v50, s13, v193, v200
	s_movk_i32 s13, 0x4800
	v_add3_u32 v51, s13, v205, v201
	v_add3_u32 v52, s13, v205, v202
	s_waitcnt vmcnt(5)
	ds_write_b128 v48, v[212:215]
	ds_write_b128 v49, v[216:219]
	ds_write_b128 v50, v[220:223]
	ds_write_b128 v51, v[224:227] offset:53248
	ds_write_b128 v52, v[228:231] offset:53248
	s_waitcnt lgkmcnt(0)
	s_barrier
	s_add_i32 s13, s12, 4
	s_cmp_lt_u32 s13, s41
	s_cbranch_scc0 .Lmy_pa1_nold
	s_add_i32 s13, s12, 3
	s_mul_i32 s44, s13, 0x30000
	s_lshl_b32 s46, s13, 17
	s_add_u32 s44, s16, s44
	s_addc_u32 s45, s17, 0
	s_add_u32 s46, s18, s46
	s_addc_u32 s47, s19, 0
	v_lshl_add_u64 v[48:49], v[132:133], 1, s[44:45]
	v_lshl_add_u64 v[50:51], v[134:135], 1, s[44:45]
	v_lshl_add_u64 v[52:53], v[136:137], 1, s[44:45]
	v_lshl_add_u64 v[54:55], v[138:139], 1, s[46:47]
	v_lshl_add_u64 v[56:57], v[140:141], 1, s[46:47]
	global_load_dwordx4 v[212:215], v[48:49], off
	global_load_dwordx4 v[216:219], v[50:51], off
	global_load_dwordx4 v[220:223], v[52:53], off
	global_load_dwordx4 v[224:227], v[54:55], off
	global_load_dwordx4 v[228:231], v[56:57], off
.Lmy_pa1_nold:
	v_mad_u32_u24 v184, v124, s28, v240
	v_add_u32_e32 v185, 0x2400, v241
	ds_read_b128 v[186:189], v184
	ds_read_b128 v[242:245], v184 offset:6656
	ds_read_b128 v[246:249], v184 offset:32
	ds_read_b128 v[250:253], v184 offset:6688
	ds_read_b128 v[176:179], v184 offset:64
	ds_read_b128 v[180:183], v184 offset:6720
	s_waitcnt lgkmcnt(5)
	v_mfma_f32_32x32x16_bf16 v[48:63], v[186:189], v[84:87], v[0:15]
	ds_read_b128 v[186:189], v184 offset:96
	s_waitcnt lgkmcnt(5)
	v_mfma_f32_32x32x16_bf16 v[64:79], v[242:245], v[84:87], v[0:15]
	ds_read_b128 v[242:245], v184 offset:6752
	s_waitcnt lgkmcnt(5)
	v_mfma_f32_32x32x16_bf16 v[48:63], v[246:249], v[88:91], v[48:63]
	ds_read_b128 v[246:249], v184 offset:128
	s_waitcnt lgkmcnt(5)
	v_mfma_f32_32x32x16_bf16 v[64:79], v[250:253], v[88:91], v[64:79]
	ds_read_b128 v[250:253], v184 offset:6784
	s_waitcnt lgkmcnt(5)
	v_mfma_f32_32x32x16_bf16 v[48:63], v[176:179], v[92:95], v[48:63]
	ds_read_b128 v[176:179], v184 offset:160
	s_waitcnt lgkmcnt(5)
	v_mfma_f32_32x32x16_bf16 v[64:79], v[180:183], v[92:95], v[64:79]
	ds_read_b128 v[180:183], v184 offset:6816
	s_waitcnt lgkmcnt(5)
	v_mfma_f32_32x32x16_bf16 v[48:63], v[186:189], v[96:99], v[48:63]
	ds_read_b128 v[186:189], v184 offset:13312
	s_waitcnt lgkmcnt(5)
	v_mfma_f32_32x32x16_bf16 v[64:79], v[242:245], v[96:99], v[64:79]
	ds_read_b128 v[242:245], v184 offset:19968
	s_waitcnt lgkmcnt(5)
	v_mfma_f32_32x32x16_bf16 v[48:63], v[246:249], v[100:103], v[48:63]
	ds_read_b128 v[246:249], v184 offset:13344
	s_waitcnt lgkmcnt(5)
	v_mfma_f32_32x32x16_bf16 v[64:79], v[250:253], v[100:103], v[64:79]
	ds_read_b128 v[250:253], v184 offset:20000
	s_waitcnt lgkmcnt(5)
	v_mfma_f32_32x32x16_bf16 v[48:63], v[176:179], v[112:115], v[48:63]
	ds_read_b128 v[176:179], v184 offset:13376
	s_waitcnt lgkmcnt(5)
	v_mfma_f32_32x32x16_bf16 v[64:79], v[180:183], v[112:115], v[64:79]
	ds_read_b128 v[180:183], v184 offset:20032
	s_waitcnt lgkmcnt(5)
	v_mfma_f32_32x32x16_bf16 v[144:159], v[186:189], v[84:87], v[0:15]
	ds_read_b128 v[186:189], v184 offset:13408
	s_waitcnt lgkmcnt(5)
	v_mfma_f32_32x32x16_bf16 v[160:175], v[242:245], v[84:87], v[0:15]
	ds_read_b128 v[242:245], v184 offset:20064
	s_nop 4
	v_exp_f32_e32 v48, v48
	v_exp_f32_e32 v49, v49
	v_exp_f32_e32 v50, v50
	s_waitcnt lgkmcnt(5)
	v_mfma_f32_32x32x16_bf16 v[144:159], v[246:249], v[88:91], v[144:159]
	ds_read_b128 v[246:249], v184 offset:13440
	v_exp_f32_e32 v51, v51
	v_exp_f32_e32 v52, v52
	v_exp_f32_e32 v53, v53
	s_waitcnt lgkmcnt(5)
	v_mfma_f32_32x32x16_bf16 v[160:175], v[250:253], v[88:91], v[160:175]
	ds_read_b128 v[250:253], v184 offset:20096
	v_exp_f32_e32 v54, v54
	v_exp_f32_e32 v55, v55
	v_exp_f32_e32 v56, v56
	s_waitcnt lgkmcnt(5)
	v_mfma_f32_32x32x16_bf16 v[144:159], v[176:179], v[92:95], v[144:159]
	ds_read_b128 v[176:179], v184 offset:13472
	v_exp_f32_e32 v57, v57
	v_exp_f32_e32 v58, v58
	v_exp_f32_e32 v59, v59
	s_waitcnt lgkmcnt(5)
	v_mfma_f32_32x32x16_bf16 v[160:175], v[180:183], v[92:95], v[160:175]
	ds_read_b128 v[180:183], v184 offset:20128
	v_exp_f32_e32 v60, v60
	v_exp_f32_e32 v61, v61
	v_exp_f32_e32 v62, v62
	s_waitcnt lgkmcnt(5)
	v_mfma_f32_32x32x16_bf16 v[144:159], v[186:189], v[96:99], v[144:159]
	ds_read_b64_tr_b16 v[186:187], v241 offset:53248
	ds_read_b64_tr_b16 v[188:189], v241 offset:54400
	v_exp_f32_e32 v63, v63
	v_exp_f32_e32 v64, v64
	v_exp_f32_e32 v65, v65
	s_waitcnt lgkmcnt(6)
	v_mfma_f32_32x32x16_bf16 v[160:175], v[242:245], v[96:99], v[160:175]
	ds_read_b64_tr_b16 v[242:243], v241 offset:53312
	ds_read_b64_tr_b16 v[244:245], v241 offset:54464
	v_exp_f32_e32 v66, v66
	v_exp_f32_e32 v67, v67
	v_exp_f32_e32 v68, v68
	s_waitcnt lgkmcnt(7)
	v_mfma_f32_32x32x16_bf16 v[144:159], v[246:249], v[100:103], v[144:159]
	ds_read_b64_tr_b16 v[246:247], v241 offset:55552
	ds_read_b64_tr_b16 v[248:249], v241 offset:56704
	v_exp_f32_e32 v69, v69
	v_exp_f32_e32 v70, v70
	v_exp_f32_e32 v71, v71
	s_waitcnt lgkmcnt(8)
	v_mfma_f32_32x32x16_bf16 v[160:175], v[250:253], v[100:103], v[160:175]
	ds_read_b64_tr_b16 v[250:251], v241 offset:55616
	ds_read_b64_tr_b16 v[252:253], v241 offset:56768
	v_exp_f32_e32 v72, v72
	v_exp_f32_e32 v73, v73
	v_exp_f32_e32 v74, v74
	s_waitcnt lgkmcnt(9)
	v_mfma_f32_32x32x16_bf16 v[144:159], v[176:179], v[112:115], v[144:159]
	v_cvt_pk_bf16_f32 v176, v48, v49
	v_cvt_pk_bf16_f32 v177, v50, v51
	v_cvt_pk_bf16_f32 v178, v52, v53
	v_cvt_pk_bf16_f32 v179, v54, v55
	v_exp_f32_e32 v75, v75
	s_waitcnt lgkmcnt(8)
	v_mfma_f32_32x32x16_bf16 v[160:175], v[180:183], v[112:115], v[160:175]
	v_exp_f32_e32 v76, v76
	v_exp_f32_e32 v77, v77
	v_exp_f32_e32 v78, v78
	s_waitcnt lgkmcnt(6)
	v_mfma_f32_32x32x16_bf16 v[16:31], v[176:179], v[186:189], v[16:31]
	ds_read_b64_tr_b16 v[186:187], v241 offset:57856
	ds_read_b64_tr_b16 v[188:189], v241 offset:59008
	v_cvt_pk_bf16_f32 v180, v56, v57
	v_cvt_pk_bf16_f32 v181, v58, v59
	v_cvt_pk_bf16_f32 v182, v60, v61
	v_cvt_pk_bf16_f32 v183, v62, v63
	v_exp_f32_e32 v79, v79
	v_exp_f32_e32 v144, v144
	s_waitcnt lgkmcnt(6)
	v_mfma_f32_32x32x16_bf16 v[32:47], v[176:179], v[242:245], v[32:47]
	ds_read_b64_tr_b16 v[242:243], v241 offset:57920
	ds_read_b64_tr_b16 v[244:245], v241 offset:59072
	v_cvt_pk_bf16_f32 v176, v64, v65
	v_cvt_pk_bf16_f32 v177, v66, v67
	v_cvt_pk_bf16_f32 v178, v68, v69
	v_cvt_pk_bf16_f32 v179, v70, v71
	v_exp_f32_e32 v145, v145
	v_exp_f32_e32 v146, v146
	s_waitcnt lgkmcnt(6)
	v_mfma_f32_32x32x16_bf16 v[16:31], v[180:183], v[246:249], v[16:31]
	ds_read_b64_tr_b16 v[246:247], v241 offset:60160
	ds_read_b64_tr_b16 v[248:249], v241 offset:61312
	v_exp_f32_e32 v147, v147
	v_exp_f32_e32 v148, v148
	v_exp_f32_e32 v149, v149
	v_exp_f32_e32 v150, v150
	s_waitcnt lgkmcnt(6)
	v_mfma_f32_32x32x16_bf16 v[32:47], v[180:183], v[250:253], v[32:47]
	ds_read_b64_tr_b16 v[250:251], v241 offset:60224
	ds_read_b64_tr_b16 v[252:253], v241 offset:61376
	v_cvt_pk_bf16_f32 v180, v72, v73
	v_cvt_pk_bf16_f32 v181, v74, v75
	v_cvt_pk_bf16_f32 v182, v76, v77
	v_cvt_pk_bf16_f32 v183, v78, v79
	v_exp_f32_e32 v151, v151
	v_exp_f32_e32 v152, v152
	s_waitcnt lgkmcnt(6)
	v_mfma_f32_32x32x16_bf16 v[16:31], v[176:179], v[186:189], v[16:31]
	ds_read_b64_tr_b16 v[186:187], v185 offset:53248
	ds_read_b64_tr_b16 v[188:189], v185 offset:54400
	v_exp_f32_e32 v153, v153
	v_exp_f32_e32 v154, v154
	v_exp_f32_e32 v155, v155
	v_exp_f32_e32 v156, v156
	s_waitcnt lgkmcnt(6)
	v_mfma_f32_32x32x16_bf16 v[32:47], v[176:179], v[242:245], v[32:47]
	ds_read_b64_tr_b16 v[242:243], v185 offset:53312
	ds_read_b64_tr_b16 v[244:245], v185 offset:54464
	v_cvt_pk_bf16_f32 v176, v144, v145
	v_cvt_pk_bf16_f32 v177, v146, v147
	v_cvt_pk_bf16_f32 v178, v148, v149
	v_cvt_pk_bf16_f32 v179, v150, v151
	v_exp_f32_e32 v157, v157
	v_exp_f32_e32 v158, v158
	s_waitcnt lgkmcnt(6)
	v_mfma_f32_32x32x16_bf16 v[16:31], v[180:183], v[246:249], v[16:31]
	ds_read_b64_tr_b16 v[246:247], v185 offset:55552
	ds_read_b64_tr_b16 v[248:249], v185 offset:56704
	v_exp_f32_e32 v159, v159
	v_exp_f32_e32 v160, v160
	v_exp_f32_e32 v161, v161
	v_exp_f32_e32 v162, v162
	s_waitcnt lgkmcnt(6)
	v_mfma_f32_32x32x16_bf16 v[32:47], v[180:183], v[250:253], v[32:47]
	ds_read_b64_tr_b16 v[250:251], v185 offset:55616
	ds_read_b64_tr_b16 v[252:253], v185 offset:56768
	v_cvt_pk_bf16_f32 v180, v152, v153
	v_cvt_pk_bf16_f32 v181, v154, v155
	v_cvt_pk_bf16_f32 v182, v156, v157
	v_cvt_pk_bf16_f32 v183, v158, v159
	v_exp_f32_e32 v163, v163
	v_exp_f32_e32 v164, v164
	s_waitcnt lgkmcnt(6)
	v_mfma_f32_32x32x16_bf16 v[16:31], v[176:179], v[186:189], v[16:31]
	ds_read_b64_tr_b16 v[186:187], v185 offset:57856
	ds_read_b64_tr_b16 v[188:189], v185 offset:59008
	v_exp_f32_e32 v165, v165
	v_exp_f32_e32 v166, v166
	v_exp_f32_e32 v167, v167
	v_exp_f32_e32 v168, v168
	s_waitcnt lgkmcnt(6)
	v_mfma_f32_32x32x16_bf16 v[32:47], v[176:179], v[242:245], v[32:47]
	ds_read_b64_tr_b16 v[242:243], v185 offset:57920
	ds_read_b64_tr_b16 v[244:245], v185 offset:59072
	v_cvt_pk_bf16_f32 v176, v160, v161
	v_cvt_pk_bf16_f32 v177, v162, v163
	v_cvt_pk_bf16_f32 v178, v164, v165
	v_cvt_pk_bf16_f32 v179, v166, v167
	v_exp_f32_e32 v169, v169
	v_exp_f32_e32 v170, v170
	s_waitcnt lgkmcnt(6)
	v_mfma_f32_32x32x16_bf16 v[16:31], v[180:183], v[246:249], v[16:31]
	ds_read_b64_tr_b16 v[246:247], v185 offset:60160
	ds_read_b64_tr_b16 v[248:249], v185 offset:61312
	v_exp_f32_e32 v171, v171
	v_exp_f32_e32 v172, v172
	v_exp_f32_e32 v173, v173
	v_exp_f32_e32 v174, v174
	s_waitcnt lgkmcnt(6)
	v_mfma_f32_32x32x16_bf16 v[32:47], v[180:183], v[250:253], v[32:47]
	ds_read_b64_tr_b16 v[250:251], v185 offset:60224
	ds_read_b64_tr_b16 v[252:253], v185 offset:61376
	v_exp_f32_e32 v175, v175
	v_cvt_pk_bf16_f32 v180, v168, v169
	v_cvt_pk_bf16_f32 v181, v170, v171
	v_cvt_pk_bf16_f32 v182, v172, v173
	v_cvt_pk_bf16_f32 v183, v174, v175
	v_add_f32_e32 v184, v48, v64
	v_add_f32_e32 v184, v184, v49
	s_waitcnt lgkmcnt(6)
	v_mfma_f32_32x32x16_bf16 v[16:31], v[176:179], v[186:189], v[16:31]
	v_add_f32_e32 v184, v184, v65
	v_add_f32_e32 v184, v184, v50
	v_add_f32_e32 v184, v184, v66
	v_add_f32_e32 v184, v184, v51
	v_add_f32_e32 v184, v184, v67
	v_add_f32_e32 v184, v184, v52
	v_add_f32_e32 v184, v184, v68
	v_add_f32_e32 v184, v184, v53
	s_waitcnt lgkmcnt(4)
	v_mfma_f32_32x32x16_bf16 v[32:47], v[176:179], v[242:245], v[32:47]
	v_add_f32_e32 v184, v184, v69
	v_add_f32_e32 v184, v184, v54
	v_add_f32_e32 v184, v184, v70
	v_add_f32_e32 v184, v184, v55
	v_add_f32_e32 v184, v184, v71
	v_add_f32_e32 v184, v184, v56
	v_add_f32_e32 v184, v184, v72
	v_add_f32_e32 v184, v184, v57
	s_waitcnt lgkmcnt(2)
	v_mfma_f32_32x32x16_bf16 v[16:31], v[180:183], v[246:249], v[16:31]
	v_add_f32_e32 v184, v184, v73
	v_add_f32_e32 v184, v184, v58
	v_add_f32_e32 v184, v184, v74
	v_add_f32_e32 v184, v184, v59
	v_add_f32_e32 v184, v184, v75
	v_add_f32_e32 v184, v184, v60
	v_add_f32_e32 v184, v184, v76
	v_add_f32_e32 v184, v184, v61
	s_waitcnt lgkmcnt(0)
	v_mfma_f32_32x32x16_bf16 v[32:47], v[180:183], v[250:253], v[32:47]
	v_add_f32_e32 v184, v184, v77
	v_add_f32_e32 v184, v184, v62
	v_add_f32_e32 v184, v184, v78
	v_add_f32_e32 v184, v184, v63
	v_add_f32_e32 v184, v184, v79
	v_add_f32_e32 v184, v184, v144
	v_add_f32_e32 v184, v184, v160
	v_add_f32_e32 v184, v184, v145
	v_add_f32_e32 v184, v184, v161
	v_add_f32_e32 v184, v184, v146
	v_add_f32_e32 v184, v184, v162
	v_add_f32_e32 v184, v184, v147
	v_add_f32_e32 v184, v184, v163
	v_add_f32_e32 v184, v184, v148
	v_add_f32_e32 v184, v184, v164
	v_add_f32_e32 v184, v184, v149
	v_add_f32_e32 v184, v184, v165
	v_add_f32_e32 v184, v184, v150
	v_add_f32_e32 v184, v184, v166
	v_add_f32_e32 v184, v184, v151
	v_add_f32_e32 v184, v184, v167
	v_add_f32_e32 v184, v184, v152
	v_add_f32_e32 v184, v184, v168
	v_add_f32_e32 v184, v184, v153
	v_add_f32_e32 v184, v184, v169
	v_add_f32_e32 v184, v184, v154
	v_add_f32_e32 v184, v184, v170
	v_add_f32_e32 v184, v184, v155
	v_add_f32_e32 v184, v184, v171
	v_add_f32_e32 v184, v184, v156
	v_add_f32_e32 v184, v184, v172
	v_add_f32_e32 v184, v184, v157
	v_add_f32_e32 v184, v184, v173
	v_add_f32_e32 v184, v184, v158
	v_add_f32_e32 v184, v184, v174
	v_add_f32_e32 v184, v184, v159
	v_add_f32_e32 v184, v184, v175
	v_add_f32_e32 v239, v239, v184
	s_add_i32 s12, s12, 2
	s_add_i32 s13, s12, 2
	s_cmp_lt_u32 s13, s41
	s_cbranch_scc1 .Lmy_pa1_pair
	v_subrev_u32_e32 v211, 32, v210
	v_subrev_u32_e32 v212, 33, v210
	v_subrev_u32_e32 v213, 34, v210
	v_subrev_u32_e32 v214, 35, v210
	v_add_u32_e32 v215, -8, v210
	v_subrev_u32_e32 v216, 40, v210
	v_add_u32_e32 v217, -9, v210
	v_subrev_u32_e32 v218, 41, v210
	v_add_u32_e32 v219, -10, v210
	v_subrev_u32_e32 v220, 42, v210
	v_add_u32_e32 v221, -11, v210
	v_subrev_u32_e32 v222, 43, v210
	v_add_u32_e32 v223, -16, v210
	v_subrev_u32_e32 v224, 48, v210
	v_subrev_u32_e32 v225, 17, v210
	v_subrev_u32_e32 v226, 49, v210
	v_subrev_u32_e32 v227, 18, v210
	v_subrev_u32_e32 v228, 50, v210
	v_subrev_u32_e32 v229, 19, v210
	v_subrev_u32_e32 v230, 51, v210
	v_subrev_u32_e32 v231, 24, v210
	v_subrev_u32_e32 v232, 56, v210
	v_subrev_u32_e32 v233, 25, v210
	v_subrev_u32_e32 v234, 57, v210
	v_subrev_u32_e32 v235, 26, v210
	v_subrev_u32_e32 v236, 58, v210
	v_subrev_u32_e32 v237, 27, v210
	v_subrev_u32_e32 v238, 59, v210
.Lmy_pa1_skip:
.LBB0_1552:
	s_and_b32 s1, s12, 1
	s_mul_i32 s0, s1, 0x6800
	s_add_i32 s6, s0, 0
	v_add3_u32 v48, s6, v125, v190
	s_waitcnt vmcnt(3)
	ds_write_b128 v48, v[104:107]
	v_add3_u32 v48, s6, v191, v192
	s_waitcnt vmcnt(2)
	ds_write_b128 v48, v[108:111]
	v_add3_u32 v48, s6, v193, v200
	s_mulk_i32 s1, 0x4800
	s_waitcnt vmcnt(1)
	ds_write_b128 v48, v[116:119]
	v_add_u32_e32 v48, s1, v205
	s_add_i32 s6, s12, 1
	v_add_u32_e32 v49, v48, v201
	v_add_u32_e32 v48, v48, v202
	s_cmp_ge_u32 s6, s41
	s_waitcnt vmcnt(0)
	ds_write_b128 v49, v[120:123] offset:53248
	ds_write_b128 v48, v[80:83] offset:53248
	s_waitcnt lgkmcnt(0)
	s_barrier
	s_cbranch_scc1 .LBB0_1554
	s_mul_i32 s44, s6, 0x30000
	s_mul_hi_u32 s13, s6, 0x30000
	s_add_u32 s44, s16, s44
	s_addc_u32 s45, s17, s13
	s_lshl_b64 s[46:47], s[6:7], 17
	v_lshl_add_u64 v[48:49], v[132:133], 1, s[44:45]
	v_lshl_add_u64 v[50:51], v[134:135], 1, s[44:45]
	global_load_dwordx4 v[104:107], v[48:49], off
	global_load_dwordx4 v[108:111], v[50:51], off
	v_lshl_add_u64 v[48:49], v[136:137], 1, s[44:45]
	s_add_u32 s44, s18, s46
	s_addc_u32 s45, s19, s47
	v_lshl_add_u64 v[50:51], v[138:139], 1, s[44:45]
	global_load_dwordx4 v[116:119], v[48:49], off
	global_load_dwordx4 v[120:123], v[50:51], off
	v_lshl_add_u64 v[48:49], v[140:141], 1, s[44:45]
	global_load_dwordx4 v[80:83], v[48:49], off

.LBB0_1564:
	s_or_b64 exec, exec, s[0:1]
	s_waitcnt lgkmcnt(0)
	ds_read_b128 v[50:53], v207
	ds_read_b128 v[54:57], v207 offset:32
	s_lshl_b64 s[0:1], s[22:23], 10
	s_add_u32 s6, s29, s0
	s_addc_u32 s12, s30, s1
	s_waitcnt lgkmcnt(1)
	v_div_scale_f32 v58, s[0:1], v50, v50, 1.0
	v_rcp_f32_e32 v59, v58
	s_lshl_b32 s22, s40, 1
	s_add_u32 s0, s6, s22
	s_addc_u32 s1, s12, 0
	v_fma_f32 v60, -v58, v59, 1.0
	v_fmac_f32_e32 v59, v60, v59
	v_div_scale_f32 v60, vcc, 1.0, v50, 1.0
	v_mul_f32_e32 v61, v60, v59
	v_fma_f32 v62, -v58, v61, v60
	v_fmac_f32_e32 v61, v62, v59
	v_fma_f32 v58, -v58, v61, v60
	v_div_fmas_f32 v58, v58, v59, v61
	v_div_fixup_f32 v50, v58, v50, 1.0
	v_mul_f32_e32 v16, v16, v50
	v_lshl_add_u64 v[48:49], s[0:1], 0, v[126:127]
	v_bfe_u32 v58, v16, 16, 1
	v_add3_u32 v16, v16, v58, s35
	v_lshl_add_u64 v[58:59], v[48:49], 0, v[144:145]
	global_store_short_d16_hi v[58:59], v16, off
	v_mul_f32_e32 v16, v32, v50
	v_div_scale_f32 v32, s[0:1], v51, v51, 1.0
	v_rcp_f32_e32 v50, v32
	v_bfe_u32 v60, v16, 16, 1
	v_add3_u32 v16, v16, v60, s35
	global_store_short_d16_hi v[58:59], v16, off offset:64
	v_fma_f32 v16, -v32, v50, 1.0
	v_fmac_f32_e32 v50, v16, v50
	v_div_scale_f32 v16, vcc, 1.0, v51, 1.0
	v_mul_f32_e32 v58, v16, v50
	v_fma_f32 v59, -v32, v58, v16
	v_fmac_f32_e32 v58, v59, v50
	v_fma_f32 v16, -v32, v58, v16
	v_div_fmas_f32 v16, v16, v50, v58
	v_div_fixup_f32 v32, v16, v51, 1.0
	v_mul_f32_e32 v16, v17, v32
	v_bfe_u32 v17, v16, 16, 1
	v_add3_u32 v50, v16, v17, s35
	v_lshl_add_u64 v[16:17], v[48:49], 0, v[146:147]
	v_mul_f32_e32 v32, v33, v32
	v_div_scale_f32 v33, s[0:1], v52, v52, 1.0
	global_store_short_d16_hi v[16:17], v50, off
	v_rcp_f32_e32 v50, v33
	v_bfe_u32 v51, v32, 16, 1
	v_add3_u32 v32, v32, v51, s35
	global_store_short_d16_hi v[16:17], v32, off offset:64
	v_fma_f32 v16, -v33, v50, 1.0
	v_fmac_f32_e32 v50, v16, v50
	v_div_scale_f32 v16, vcc, 1.0, v52, 1.0
	v_mul_f32_e32 v17, v16, v50
	v_fma_f32 v32, -v33, v17, v16
	v_fmac_f32_e32 v17, v32, v50
	v_fma_f32 v16, -v33, v17, v16
	v_div_fmas_f32 v16, v16, v50, v17
	v_div_fixup_f32 v32, v16, v52, 1.0
	v_mul_f32_e32 v16, v18, v32
	v_bfe_u32 v17, v16, 16, 1
	v_add3_u32 v18, v16, v17, s35
	v_lshl_add_u64 v[16:17], v[48:49], 0, v[148:149]
	global_store_short_d16_hi v[16:17], v18, off
	v_mul_f32_e32 v18, v34, v32
	v_div_scale_f32 v32, s[0:1], v53, v53, 1.0
	v_rcp_f32_e32 v33, v32
	v_bfe_u32 v34, v18, 16, 1
	v_add3_u32 v18, v18, v34, s35
	global_store_short_d16_hi v[16:17], v18, off offset:64
	v_fma_f32 v16, -v32, v33, 1.0
	v_fmac_f32_e32 v33, v16, v33
	v_div_scale_f32 v16, vcc, 1.0, v53, 1.0
	v_mul_f32_e32 v17, v16, v33
	v_fma_f32 v18, -v32, v17, v16
	v_fmac_f32_e32 v17, v18, v33
	v_fma_f32 v16, -v32, v17, v16
	v_div_fmas_f32 v16, v16, v33, v17
	v_div_fixup_f32 v18, v16, v53, 1.0
	v_mul_f32_e32 v16, v19, v18
	v_bfe_u32 v17, v16, 16, 1
	v_add3_u32 v19, v16, v17, s35
	v_lshl_add_u64 v[16:17], v[48:49], 0, v[150:151]
	global_store_short_d16_hi v[16:17], v19, off
	s_waitcnt lgkmcnt(0)
	v_div_scale_f32 v19, s[0:1], v54, v54, 1.0
	v_rcp_f32_e32 v32, v19
	v_mul_f32_e32 v18, v35, v18
	v_bfe_u32 v33, v18, 16, 1
	v_add3_u32 v18, v18, v33, s35
	global_store_short_d16_hi v[16:17], v18, off offset:64
	v_fma_f32 v16, -v19, v32, 1.0
	v_fmac_f32_e32 v32, v16, v32
	v_div_scale_f32 v16, vcc, 1.0, v54, 1.0
	v_mul_f32_e32 v17, v16, v32
	v_fma_f32 v18, -v19, v17, v16
	v_fmac_f32_e32 v17, v18, v32
	v_fma_f32 v16, -v19, v17, v16
	v_div_fmas_f32 v16, v16, v32, v17
	v_div_fixup_f32 v18, v16, v54, 1.0
	v_mul_f32_e32 v16, v20, v18
	v_bfe_u32 v17, v16, 16, 1
	v_add3_u32 v19, v16, v17, s35
	v_lshl_add_u64 v[16:17], v[48:49], 0, v[152:153]
	global_store_short_d16_hi v[16:17], v19, off
	v_div_scale_f32 v19, s[0:1], v55, v55, 1.0
	v_rcp_f32_e32 v20, v19
	v_mul_f32_e32 v18, v36, v18
	v_bfe_u32 v32, v18, 16, 1
	v_add3_u32 v18, v18, v32, s35
	global_store_short_d16_hi v[16:17], v18, off offset:64
	v_fma_f32 v16, -v19, v20, 1.0
	v_fmac_f32_e32 v20, v16, v20
	v_div_scale_f32 v16, vcc, 1.0, v55, 1.0
	v_mul_f32_e32 v17, v16, v20
	v_fma_f32 v18, -v19, v17, v16
	v_fmac_f32_e32 v17, v18, v20
	v_fma_f32 v16, -v19, v17, v16
	v_div_fmas_f32 v16, v16, v20, v17
	v_div_fixup_f32 v18, v16, v55, 1.0
	v_mul_f32_e32 v16, v21, v18
	v_bfe_u32 v17, v16, 16, 1
	v_add3_u32 v19, v16, v17, s35
	v_lshl_add_u64 v[16:17], v[48:49], 0, v[154:155]
	global_store_short_d16_hi v[16:17], v19, off
	v_div_scale_f32 v19, s[0:1], v56, v56, 1.0
	v_rcp_f32_e32 v20, v19
	v_mul_f32_e32 v18, v37, v18
	v_bfe_u32 v21, v18, 16, 1
	v_add3_u32 v18, v18, v21, s35
	global_store_short_d16_hi v[16:17], v18, off offset:64
	v_fma_f32 v16, -v19, v20, 1.0
	v_fmac_f32_e32 v20, v16, v20
	v_div_scale_f32 v16, vcc, 1.0, v56, 1.0
	v_mul_f32_e32 v17, v16, v20
	v_fma_f32 v18, -v19, v17, v16
	v_fmac_f32_e32 v17, v18, v20
	v_fma_f32 v16, -v19, v17, v16
	v_div_fmas_f32 v16, v16, v20, v17
	v_div_fixup_f32 v18, v16, v56, 1.0
	v_mul_f32_e32 v16, v22, v18
	v_bfe_u32 v17, v16, 16, 1
	v_add3_u32 v19, v16, v17, s35
	v_lshl_add_u64 v[16:17], v[48:49], 0, v[156:157]
	global_store_short_d16_hi v[16:17], v19, off
	v_div_scale_f32 v19, s[0:1], v57, v57, 1.0
	v_rcp_f32_e32 v20, v19
	v_mul_f32_e32 v18, v38, v18
	v_bfe_u32 v21, v18, 16, 1
	v_add3_u32 v18, v18, v21, s35
	global_store_short_d16_hi v[16:17], v18, off offset:64
	v_fma_f32 v16, -v19, v20, 1.0
	v_fmac_f32_e32 v20, v16, v20
	v_div_scale_f32 v16, vcc, 1.0, v57, 1.0
	v_mul_f32_e32 v17, v16, v20
	v_fma_f32 v18, -v19, v17, v16
	v_fmac_f32_e32 v17, v18, v20
	v_fma_f32 v16, -v19, v17, v16
	v_div_fmas_f32 v16, v16, v20, v17
	v_div_fixup_f32 v20, v16, v57, 1.0
	v_mul_f32_e32 v16, v23, v20
	v_bfe_u32 v17, v16, 16, 1
	v_add3_u32 v21, v16, v17, s35
	ds_read_b128 v[16:19], v207 offset:64
	v_lshl_add_u64 v[32:33], v[48:49], 0, v[158:159]
	global_store_short_d16_hi v[32:33], v21, off
	v_mul_f32_e32 v34, v39, v20
	ds_read_b128 v[20:23], v207 offset:96
	s_waitcnt lgkmcnt(1)
	v_div_scale_f32 v35, s[0:1], v16, v16, 1.0
	v_rcp_f32_e32 v36, v35
	v_bfe_u32 v37, v34, 16, 1
	v_add3_u32 v34, v34, v37, s35
	global_store_short_d16_hi v[32:33], v34, off offset:64
	v_fma_f32 v32, -v35, v36, 1.0
	v_fmac_f32_e32 v36, v32, v36
	v_div_scale_f32 v32, vcc, 1.0, v16, 1.0
	v_mul_f32_e32 v33, v32, v36
	v_fma_f32 v34, -v35, v33, v32
	v_fmac_f32_e32 v33, v34, v36
	v_fma_f32 v32, -v35, v33, v32
	v_div_fmas_f32 v32, v32, v36, v33
	v_div_fixup_f32 v16, v32, v16, 1.0
	v_mul_f32_e32 v24, v24, v16
	v_bfe_u32 v32, v24, 16, 1
	v_add3_u32 v24, v24, v32, s35
	v_lshl_add_u64 v[32:33], v[48:49], 0, v[160:161]
	global_store_short_d16_hi v[32:33], v24, off
	v_div_scale_f32 v24, s[0:1], v17, v17, 1.0
	v_rcp_f32_e32 v34, v24
	v_mul_f32_e32 v16, v40, v16
	v_bfe_u32 v35, v16, 16, 1
	v_add3_u32 v16, v16, v35, s35
	global_store_short_d16_hi v[32:33], v16, off offset:64
	v_fma_f32 v16, -v24, v34, 1.0
	v_fmac_f32_e32 v34, v16, v34
	v_div_scale_f32 v16, vcc, 1.0, v17, 1.0
	v_mul_f32_e32 v32, v16, v34
	v_fma_f32 v33, -v24, v32, v16
	v_fmac_f32_e32 v32, v33, v34
	v_fma_f32 v16, -v24, v32, v16
	v_div_fmas_f32 v16, v16, v34, v32
	v_div_fixup_f32 v24, v16, v17, 1.0
	v_mul_f32_e32 v16, v25, v24
	v_bfe_u32 v17, v16, 16, 1
	v_add3_u32 v25, v16, v17, s35
	v_lshl_add_u64 v[16:17], v[48:49], 0, v[162:163]
	global_store_short_d16_hi v[16:17], v25, off
	v_div_scale_f32 v25, s[0:1], v18, v18, 1.0
	v_rcp_f32_e32 v32, v25
	v_mul_f32_e32 v24, v41, v24
	v_bfe_u32 v33, v24, 16, 1
	v_add3_u32 v24, v24, v33, s35
	global_store_short_d16_hi v[16:17], v24, off offset:64
	v_fma_f32 v16, -v25, v32, 1.0
	v_fmac_f32_e32 v32, v16, v32
	v_div_scale_f32 v16, vcc, 1.0, v18, 1.0
	v_mul_f32_e32 v17, v16, v32
	v_fma_f32 v24, -v25, v17, v16
	v_fmac_f32_e32 v17, v24, v32
	v_fma_f32 v16, -v25, v17, v16
	v_div_fmas_f32 v16, v16, v32, v17
	v_div_fixup_f32 v18, v16, v18, 1.0
	v_mul_f32_e32 v16, v26, v18
	v_bfe_u32 v17, v16, 16, 1
	v_add3_u32 v24, v16, v17, s35
	v_lshl_add_u64 v[16:17], v[48:49], 0, v[164:165]
	global_store_short_d16_hi v[16:17], v24, off
	v_div_scale_f32 v24, s[0:1], v19, v19, 1.0
	v_rcp_f32_e32 v25, v24
	v_mul_f32_e32 v18, v42, v18
	v_bfe_u32 v26, v18, 16, 1
	v_add3_u32 v18, v18, v26, s35
	global_store_short_d16_hi v[16:17], v18, off offset:64
	v_fma_f32 v16, -v24, v25, 1.0
	v_fmac_f32_e32 v25, v16, v25
	v_div_scale_f32 v16, vcc, 1.0, v19, 1.0
	v_mul_f32_e32 v17, v16, v25
	v_fma_f32 v18, -v24, v17, v16
	v_fmac_f32_e32 v17, v18, v25
	v_fma_f32 v16, -v24, v17, v16
	v_div_fmas_f32 v16, v16, v25, v17
	v_div_fixup_f32 v18, v16, v19, 1.0
	v_mul_f32_e32 v16, v27, v18
	v_bfe_u32 v17, v16, 16, 1
	v_add3_u32 v19, v16, v17, s35
	v_lshl_add_u64 v[16:17], v[48:49], 0, v[166:167]
	global_store_short_d16_hi v[16:17], v19, off
	s_waitcnt lgkmcnt(0)
	v_div_scale_f32 v19, s[0:1], v20, v20, 1.0
	v_rcp_f32_e32 v24, v19
	v_mul_f32_e32 v18, v43, v18
	v_bfe_u32 v25, v18, 16, 1
	v_add3_u32 v18, v18, v25, s35
	global_store_short_d16_hi v[16:17], v18, off offset:64
	v_fma_f32 v16, -v19, v24, 1.0
	v_fmac_f32_e32 v24, v16, v24
	v_div_scale_f32 v16, vcc, 1.0, v20, 1.0
	v_mul_f32_e32 v17, v16, v24
	v_fma_f32 v18, -v19, v17, v16
	v_fmac_f32_e32 v17, v18, v24
	v_fma_f32 v16, -v19, v17, v16
	v_div_fmas_f32 v16, v16, v24, v17
	v_div_fixup_f32 v18, v16, v20, 1.0
	v_mul_f32_e32 v16, v28, v18
	v_bfe_u32 v17, v16, 16, 1
	v_add3_u32 v19, v16, v17, s35
	v_lshl_add_u64 v[16:17], v[48:49], 0, v[168:169]
	global_store_short_d16_hi v[16:17], v19, off
	v_div_scale_f32 v19, s[0:1], v21, v21, 1.0
	v_rcp_f32_e32 v20, v19
	v_mul_f32_e32 v18, v44, v18
	v_bfe_u32 v24, v18, 16, 1
	v_add3_u32 v18, v18, v24, s35
	global_store_short_d16_hi v[16:17], v18, off offset:64
	v_fma_f32 v16, -v19, v20, 1.0
	v_fmac_f32_e32 v20, v16, v20
	v_div_scale_f32 v16, vcc, 1.0, v21, 1.0
	v_mul_f32_e32 v17, v16, v20
	v_fma_f32 v18, -v19, v17, v16
	v_fmac_f32_e32 v17, v18, v20
	v_fma_f32 v16, -v19, v17, v16
	v_div_fmas_f32 v16, v16, v20, v17
	v_div_fixup_f32 v18, v16, v21, 1.0
	v_mul_f32_e32 v16, v29, v18
	v_bfe_u32 v17, v16, 16, 1
	v_add3_u32 v19, v16, v17, s35
	v_lshl_add_u64 v[16:17], v[48:49], 0, v[170:171]
	global_store_short_d16_hi v[16:17], v19, off
	v_div_scale_f32 v19, s[0:1], v22, v22, 1.0
	v_rcp_f32_e32 v20, v19
	v_mul_f32_e32 v18, v45, v18
	v_bfe_u32 v21, v18, 16, 1
	v_add3_u32 v18, v18, v21, s35
	global_store_short_d16_hi v[16:17], v18, off offset:64
	v_fma_f32 v16, -v19, v20, 1.0
	v_fmac_f32_e32 v20, v16, v20
	v_div_scale_f32 v16, vcc, 1.0, v22, 1.0
	v_mul_f32_e32 v17, v16, v20
	v_fma_f32 v18, -v19, v17, v16
	v_fmac_f32_e32 v17, v18, v20
	v_fma_f32 v16, -v19, v17, v16
	v_div_fmas_f32 v16, v16, v20, v17
	v_div_fixup_f32 v18, v16, v22, 1.0
	v_mul_f32_e32 v16, v30, v18
	v_bfe_u32 v17, v16, 16, 1
	v_add3_u32 v19, v16, v17, s35
	v_lshl_add_u64 v[16:17], v[48:49], 0, v[172:173]
	global_store_short_d16_hi v[16:17], v19, off
	v_div_scale_f32 v19, s[0:1], v23, v23, 1.0
	v_rcp_f32_e32 v20, v19
	v_mul_f32_e32 v18, v46, v18
	v_bfe_u32 v21, v18, 16, 1
	v_add3_u32 v18, v18, v21, s35
	global_store_short_d16_hi v[16:17], v18, off offset:64
	v_fma_f32 v16, -v19, v20, 1.0
	v_fmac_f32_e32 v20, v16, v20
	v_div_scale_f32 v16, vcc, 1.0, v23, 1.0
	v_mul_f32_e32 v17, v16, v20
	v_fma_f32 v18, -v19, v17, v16
	v_fmac_f32_e32 v17, v18, v20
	v_fma_f32 v16, -v19, v17, v16
	v_div_fmas_f32 v16, v16, v20, v17
	v_div_fixup_f32 v18, v16, v23, 1.0
	v_mul_f32_e32 v16, v31, v18
	v_bfe_u32 v17, v16, 16, 1
	s_xor_b32 s12, s38, 15
	v_add3_u32 v19, v16, v17, s35
	v_lshl_add_u64 v[16:17], v[48:49], 0, v[174:175]
	v_mul_f32_e32 v18, v47, v18
	s_lshl_b32 s0, s12, 8
	global_store_short_d16_hi v[16:17], v19, off
	v_bfe_u32 v19, v18, 16, 1
	s_add_i32 s13, s25, s0
	v_add3_u32 v18, v18, v19, s35
	s_add_u32 s20, s20, s13
	global_store_short_d16_hi v[16:17], v18, off offset:64
	s_addc_u32 s21, s21, 0
	v_or_b32_e32 v16, s20, v124
	v_mov_b64_e32 v[18:19], s[8:9]
	v_mov_b32_e32 v17, s21
	v_mad_u64_u32 v[18:19], s[0:1], v16, s31, v[18:19]
	v_mad_i32_i24 v19, s21, v209, v19
	s_lshl_b32 s6, s39, 1
	v_lshlrev_b64 v[16:17], 6, v[16:17]
	s_waitcnt lgkmcnt(0)
	v_lshl_add_u64 v[18:19], v[18:19], 0, s[6:7]
	v_lshl_add_u64 v[16:17], s[10:11], 0, v[16:17]
	s_lshl_b32 s6, s37, 2
	v_lshl_add_u64 v[16:17], v[16:17], 0, s[6:7]
	global_load_dword v44, v[16:17], off
	s_nop 0
	global_load_dword v16, v[16:17], off offset:32
	s_nop 0
	global_load_dwordx4 v[24:27], v[130:131], off
	global_load_dwordx4 v[28:31], v[130:131], off offset:16
	v_lshl_add_u64 v[68:69], v[128:129], 1, v[18:19]
	global_load_dwordx4 v[20:23], v[68:69], off
	global_load_dwordx4 v[32:35], v[130:131], off offset:64
	global_load_dwordx4 v[36:39], v[130:131], off offset:80
	global_load_dwordx4 v[40:43], v[68:69], off offset:32
	s_lshl_b32 s23, s12, 1
	s_add_i32 s23, s23, 2
	s_or_b32 s37, s13, 31
	s_lshl_b32 s38, s12, 2
	v_mov_b32_e32 v229, 0
	s_waitcnt vmcnt(6)
	v_add_f32_e32 v16, v44, v16
	v_fmamk_f32 v16, v16, 0x3c2aaaab, v143
	v_mul_f32_e32 v17, 0x4f800000, v16
	v_cmp_gt_f32_e32 vcc, s34, v16
	s_waitcnt vmcnt(3)
	v_lshlrev_b32_e32 v80, 16, v20
	v_and_b32_e32 v81, 0xffff0000, v20
	v_cndmask_b32_e32 v56, v16, v17, vcc
	v_sqrt_f32_e32 v57, v56
	global_load_dwordx4 v[44:47], v[130:131], off offset:128
	global_load_dwordx4 v[16:19], v[68:69], off offset:160
	global_load_dwordx4 v[48:51], v[130:131], off offset:144
	global_load_dwordx4 v[52:55], v[68:69], off offset:64
	v_lshlrev_b32_e32 v20, 16, v21
	v_and_b32_e32 v21, 0xffff0000, v21
	v_add_u32_e32 v58, -1, v57
	v_fma_f32 v59, -v58, v57, v56
	v_cmp_ge_f32_e64 s[0:1], 0, v59
	v_add_u32_e32 v59, 1, v57
	s_nop 0
	v_cndmask_b32_e64 v58, v57, v58, s[0:1]
	v_fma_f32 v57, -v59, v57, v56
	v_cmp_lt_f32_e64 s[0:1], 0, v57
	s_nop 1
	v_cndmask_b32_e64 v57, v58, v59, s[0:1]
	v_mul_f32_e32 v58, 0x37800000, v57
	v_cndmask_b32_e32 v57, v57, v58, vcc
	v_cmp_class_f32_e32 vcc, v56, v208
	s_nop 1
	v_cndmask_b32_e32 v72, v57, v56, vcc
	v_div_scale_f32 v73, s[0:1], v72, v72, 1.0
	v_rcp_f32_e32 v74, v73
	global_load_dwordx4 v[56:59], v[130:131], off offset:208
	global_load_dwordx4 v[60:63], v[130:131], off offset:192
	global_load_dwordx4 v[64:67], v[68:69], off offset:96
	s_nop 0
	global_load_dwordx4 v[68:71], v[68:69], off offset:128
	s_mov_b32 s0, 0
	v_fma_f32 v75, -v73, v74, 1.0
	v_fmac_f32_e32 v74, v75, v74
	v_div_scale_f32 v75, vcc, 1.0, v72, 1.0
	v_mul_f32_e32 v76, v75, v74
	v_fma_f32 v77, -v73, v76, v75
	v_fmac_f32_e32 v76, v77, v74
	v_fma_f32 v73, -v73, v76, v75
	v_div_fmas_f32 v73, v73, v74, v76
	v_div_fixup_f32 v72, v73, v72, 1.0
	v_pk_mul_f32 v[74:75], v[26:27], v[72:73] op_sel_hi:[1,0]
	v_pk_mul_f32 v[76:77], v[24:25], v[72:73] op_sel_hi:[1,0]
	v_pk_mul_f32 v[78:79], v[30:31], v[72:73] op_sel_hi:[1,0]
	v_pk_mul_f32 v[82:83], v[28:29], v[72:73] op_sel_hi:[1,0]
	global_load_dwordx4 v[24:27], v[130:131], off offset:272
	global_load_dwordx4 v[28:31], v[130:131], off offset:256
	global_load_dwordx4 v[84:87], v[176:177], off
	v_pk_mul_f32 v[20:21], v[74:75], v[20:21]
	v_pk_mul_f32 v[76:77], v[76:77], v[80:81]
	v_cvt_pk_bf16_f32 v81, v20, v21
	v_lshlrev_b32_e32 v20, 16, v22
	v_and_b32_e32 v21, 0xffff0000, v22
	v_pk_mul_f32 v[20:21], v[82:83], v[20:21]
	v_cvt_pk_bf16_f32 v80, v76, v77
	v_cvt_pk_bf16_f32 v82, v20, v21
	v_lshlrev_b32_e32 v20, 16, v23
	v_and_b32_e32 v21, 0xffff0000, v23
	v_pk_mul_f32 v[20:21], v[78:79], v[20:21]
	s_waitcnt vmcnt(13)
	v_pk_mul_f32 v[74:75], v[34:35], v[72:73] op_sel_hi:[1,0]
	v_cvt_pk_bf16_f32 v83, v20, v21
	v_pk_mul_f32 v[76:77], v[32:33], v[72:73] op_sel_hi:[1,0]
	global_load_dwordx4 v[20:23], v[130:131], off offset:336
	global_load_dwordx4 v[32:35], v[130:131], off offset:320
	global_load_dwordx4 v[104:107], v[178:179], off
	global_load_dwordx4 v[108:111], v[180:181], off
	global_load_dwordx4 v[116:119], v[182:183], off
	global_load_dwordx4 v[120:123], v[184:185], off
	s_waitcnt vmcnt(17)
	v_lshlrev_b32_e32 v78, 16, v40
	v_and_b32_e32 v79, 0xffff0000, v40
	v_lshlrev_b32_e32 v40, 16, v41
	v_and_b32_e32 v41, 0xffff0000, v41
	v_pk_mul_f32 v[40:41], v[74:75], v[40:41]
	v_pk_mul_f32 v[36:37], v[36:37], v[72:73] op_sel_hi:[1,0]
	v_cvt_pk_bf16_f32 v89, v40, v41
	v_lshlrev_b32_e32 v40, 16, v42
	v_and_b32_e32 v41, 0xffff0000, v42
	v_pk_mul_f32 v[36:37], v[36:37], v[40:41]
	v_pk_mul_f32 v[38:39], v[38:39], v[72:73] op_sel_hi:[1,0]
	v_cvt_pk_bf16_f32 v90, v36, v37
	v_lshlrev_b32_e32 v36, 16, v43
	v_and_b32_e32 v37, 0xffff0000, v43
	v_pk_mul_f32 v[36:37], v[38:39], v[36:37]
	v_pk_mul_f32 v[76:77], v[76:77], v[78:79]
	v_cvt_pk_bf16_f32 v91, v36, v37
	v_or_b32_e32 v180, s13, v124
	v_cvt_pk_bf16_f32 v88, v76, v77
	v_subrev_u32_e32 v181, 32, v180
	s_waitcnt vmcnt(16)
	v_pk_mul_f32 v[38:39], v[44:45], v[72:73] op_sel_hi:[1,0]
	v_pk_mul_f32 v[36:37], v[46:47], v[72:73] op_sel_hi:[1,0]
	s_waitcnt vmcnt(14)
	v_pk_mul_f32 v[42:43], v[48:49], v[72:73] op_sel_hi:[1,0]
	s_waitcnt vmcnt(13)
	v_lshlrev_b32_e32 v44, 16, v52
	v_and_b32_e32 v45, 0xffff0000, v52
	v_pk_mul_f32 v[38:39], v[38:39], v[44:45]
	v_pk_mul_f32 v[40:41], v[50:51], v[72:73] op_sel_hi:[1,0]
	v_cvt_pk_bf16_f32 v92, v38, v39
	v_lshlrev_b32_e32 v38, 16, v53
	v_and_b32_e32 v39, 0xffff0000, v53
	v_pk_mul_f32 v[36:37], v[36:37], v[38:39]
	v_subrev_u32_e32 v182, 33, v180
	v_cvt_pk_bf16_f32 v93, v36, v37
	v_lshlrev_b32_e32 v36, 16, v54
	v_and_b32_e32 v37, 0xffff0000, v54
	v_pk_mul_f32 v[36:37], v[42:43], v[36:37]
	v_subrev_u32_e32 v183, 34, v180
	v_cvt_pk_bf16_f32 v94, v36, v37
	v_lshlrev_b32_e32 v36, 16, v55
	v_and_b32_e32 v37, 0xffff0000, v55
	v_pk_mul_f32 v[36:37], v[40:41], v[36:37]
	v_subrev_u32_e32 v184, 35, v180
	v_cvt_pk_bf16_f32 v95, v36, v37
	s_waitcnt vmcnt(12)
	v_pk_mul_f32 v[42:43], v[72:73], v[56:57] op_sel_hi:[0,1]
	s_waitcnt vmcnt(11)
	v_pk_mul_f32 v[38:39], v[72:73], v[60:61] op_sel_hi:[0,1]
	s_waitcnt vmcnt(10)
	v_lshlrev_b32_e32 v44, 16, v64
	v_and_b32_e32 v45, 0xffff0000, v64
	v_pk_mul_f32 v[38:39], v[38:39], v[44:45]
	v_pk_mul_f32 v[36:37], v[72:73], v[62:63] op_sel_hi:[0,1]
	v_cvt_pk_bf16_f32 v96, v38, v39
	v_lshlrev_b32_e32 v38, 16, v65
	v_and_b32_e32 v39, 0xffff0000, v65
	v_pk_mul_f32 v[36:37], v[36:37], v[38:39]
	v_pk_mul_f32 v[40:41], v[72:73], v[58:59] op_sel_hi:[0,1]
	v_cvt_pk_bf16_f32 v97, v36, v37
	v_lshlrev_b32_e32 v36, 16, v66
	v_and_b32_e32 v37, 0xffff0000, v66
	v_pk_mul_f32 v[36:37], v[42:43], v[36:37]
	v_add_u32_e32 v185, -8, v180
	v_cvt_pk_bf16_f32 v98, v36, v37
	v_lshlrev_b32_e32 v36, 16, v67
	v_and_b32_e32 v37, 0xffff0000, v67
	v_pk_mul_f32 v[36:37], v[40:41], v[36:37]
	s_waitcnt vmcnt(7)
	v_pk_mul_f32 v[28:29], v[72:73], v[28:29] op_sel_hi:[0,1]
	v_cvt_pk_bf16_f32 v99, v36, v37
	v_lshlrev_b32_e32 v36, 16, v68
	v_and_b32_e32 v37, 0xffff0000, v68
	v_pk_mul_f32 v[28:29], v[28:29], v[36:37]
	v_pk_mul_f32 v[30:31], v[72:73], v[30:31] op_sel_hi:[0,1]
	v_cvt_pk_bf16_f32 v100, v28, v29
	v_lshlrev_b32_e32 v28, 16, v69
	v_and_b32_e32 v29, 0xffff0000, v69
	v_pk_mul_f32 v[28:29], v[30:31], v[28:29]
	v_pk_mul_f32 v[24:25], v[72:73], v[24:25] op_sel_hi:[0,1]
	v_cvt_pk_bf16_f32 v101, v28, v29
	v_lshlrev_b32_e32 v28, 16, v70
	v_and_b32_e32 v29, 0xffff0000, v70
	v_pk_mul_f32 v[24:25], v[24:25], v[28:29]
	v_pk_mul_f32 v[26:27], v[72:73], v[26:27] op_sel_hi:[0,1]
	v_cvt_pk_bf16_f32 v102, v24, v25
	v_lshlrev_b32_e32 v24, 16, v71
	v_and_b32_e32 v25, 0xffff0000, v71
	v_pk_mul_f32 v[24:25], v[26:27], v[24:25]
	v_lshlrev_b32_e32 v28, 16, v16
	v_cvt_pk_bf16_f32 v103, v24, v25
	s_waitcnt vmcnt(4)
	v_pk_mul_f32 v[24:25], v[72:73], v[34:35] op_sel_hi:[0,1]
	v_and_b32_e32 v29, 0xffff0000, v16
	v_lshlrev_b32_e32 v16, 16, v17
	v_and_b32_e32 v17, 0xffff0000, v17
	v_pk_mul_f32 v[16:17], v[24:25], v[16:17]
	v_pk_mul_f32 v[20:21], v[72:73], v[20:21] op_sel_hi:[0,1]
	v_cvt_pk_bf16_f32 v113, v16, v17
	v_lshlrev_b32_e32 v16, 16, v18
	v_and_b32_e32 v17, 0xffff0000, v18
	v_pk_mul_f32 v[16:17], v[20:21], v[16:17]
	v_pk_mul_f32 v[26:27], v[72:73], v[32:33] op_sel_hi:[0,1]
	v_pk_mul_f32 v[22:23], v[72:73], v[22:23] op_sel_hi:[0,1]
	v_cvt_pk_bf16_f32 v114, v16, v17
	v_lshlrev_b32_e32 v16, 16, v19
	v_and_b32_e32 v17, 0xffff0000, v19
	v_pk_mul_f32 v[26:27], v[26:27], v[28:29]
	v_pk_mul_f32 v[16:17], v[22:23], v[16:17]
	v_mov_b32_e32 v30, v127
	v_mov_b32_e32 v31, v127
	v_cvt_pk_bf16_f32 v112, v26, v27
	v_cvt_pk_bf16_f32 v115, v16, v17
	v_mov_b32_e32 v16, v127
	v_mov_b32_e32 v17, v127
	v_mov_b32_e32 v18, v127
	v_mov_b32_e32 v19, v127
	v_mov_b32_e32 v20, v127
	v_mov_b32_e32 v21, v127
	v_mov_b32_e32 v22, v127
	v_mov_b32_e32 v23, v127
	v_mov_b32_e32 v24, v127
	v_mov_b32_e32 v25, v127
	v_mov_b32_e32 v26, v127
	v_mov_b32_e32 v27, v127
	v_mov_b32_e32 v28, v127
	v_mov_b32_e32 v29, v127
	v_mov_b64_e32 v[46:47], v[30:31]
	v_subrev_u32_e32 v186, 40, v180
	v_add_u32_e32 v187, -9, v180
	v_subrev_u32_e32 v188, 41, v180
	v_add_u32_e32 v189, -10, v180
	v_subrev_u32_e32 v210, 42, v180
	v_add_u32_e32 v211, -11, v180
	v_subrev_u32_e32 v212, 43, v180
	v_add_u32_e32 v213, -16, v180
	v_subrev_u32_e32 v214, 48, v180
	v_subrev_u32_e32 v215, 17, v180
	v_subrev_u32_e32 v216, 49, v180
	v_subrev_u32_e32 v217, 18, v180
	v_subrev_u32_e32 v218, 50, v180
	v_subrev_u32_e32 v219, 19, v180
	v_subrev_u32_e32 v220, 51, v180
	v_subrev_u32_e32 v221, 24, v180
	v_subrev_u32_e32 v222, 56, v180
	v_subrev_u32_e32 v223, 25, v180
	v_subrev_u32_e32 v224, 57, v180
	v_subrev_u32_e32 v225, 26, v180
	v_subrev_u32_e32 v226, 58, v180
	v_subrev_u32_e32 v227, 27, v180
	v_subrev_u32_e32 v228, 59, v180
	v_mov_b64_e32 v[44:45], v[28:29]
	v_mov_b64_e32 v[42:43], v[26:27]
	v_mov_b64_e32 v[40:41], v[24:25]
	v_mov_b64_e32 v[38:39], v[22:23]
	v_mov_b64_e32 v[36:37], v[20:21]
	v_mov_b64_e32 v[34:35], v[18:19]
	v_mov_b64_e32 v[32:33], v[16:17]
	s_cmp_lt_u32 s23, 4
	s_cbranch_scc1 .Lmy_pa2_skip
	s_add_u32 s40, s16, 0x30000
	s_addc_u32 s41, s17, 0
	s_add_u32 s42, s18, 0x20000
	s_addc_u32 s43, s19, 0
	v_lshl_add_u64 v[48:49], v[132:133], 1, s[40:41]
	v_lshl_add_u64 v[50:51], v[134:135], 1, s[40:41]
	v_lshl_add_u64 v[52:53], v[136:137], 1, s[40:41]
	v_lshl_add_u64 v[54:55], v[138:139], 1, s[42:43]
	v_lshl_add_u64 v[56:57], v[140:141], 1, s[42:43]
	global_load_dwordx4 v[212:215], v[48:49], off
	global_load_dwordx4 v[216:219], v[50:51], off
	global_load_dwordx4 v[220:223], v[52:53], off
	global_load_dwordx4 v[224:227], v[54:55], off
	global_load_dwordx4 v[184:187], v[56:57], off
	v_add_u32_e32 v230, 0x6800, v203
	v_add_u32_e32 v231, 0x4800, v204
	s_mov_b32 s0, 0
.Lmy_pa2_pair:
	v_add_u32_e32 v48, v125, v190
	v_add_u32_e32 v49, v191, v192
	v_add_u32_e32 v50, v193, v200
	v_add_u32_e32 v51, v205, v201
	v_add_u32_e32 v52, v205, v202
	s_waitcnt vmcnt(5)
	ds_write_b128 v48, v[104:107]
	ds_write_b128 v49, v[108:111]
	ds_write_b128 v50, v[116:119]
	ds_write_b128 v51, v[120:123] offset:53248
	ds_write_b128 v52, v[84:87] offset:53248
	s_waitcnt lgkmcnt(0)
	s_barrier
	s_add_i32 s39, s0, 2
	s_mul_i32 s40, s39, 0x30000
	s_lshl_b32 s42, s39, 17
	s_add_u32 s40, s16, s40
	s_addc_u32 s41, s17, 0
	s_add_u32 s42, s18, s42
	s_addc_u32 s43, s19, 0
	v_lshl_add_u64 v[48:49], v[132:133], 1, s[40:41]
	v_lshl_add_u64 v[50:51], v[134:135], 1, s[40:41]
	v_lshl_add_u64 v[52:53], v[136:137], 1, s[40:41]
	v_lshl_add_u64 v[54:55], v[138:139], 1, s[42:43]
	v_lshl_add_u64 v[56:57], v[140:141], 1, s[42:43]
	global_load_dwordx4 v[104:107], v[48:49], off
	global_load_dwordx4 v[108:111], v[50:51], off
	global_load_dwordx4 v[116:119], v[52:53], off
	global_load_dwordx4 v[120:123], v[54:55], off
	global_load_dwordx4 v[84:87], v[56:57], off
	v_mad_u32_u24 v252, v124, s28, v203
	v_add_u32_e32 v253, 0x2400, v204
	ds_read_b128 v[176:179], v252
	ds_read_b128 v[232:235], v252 offset:6656
	ds_read_b128 v[236:239], v252 offset:32
	ds_read_b128 v[240:243], v252 offset:6688
	ds_read_b128 v[244:247], v252 offset:64
	ds_read_b128 v[248:251], v252 offset:6720
	s_waitcnt lgkmcnt(5)
	v_mfma_f32_32x32x16_bf16 v[48:63], v[176:179], v[80:83], v[0:15]
	ds_read_b128 v[176:179], v252 offset:96
	s_waitcnt lgkmcnt(5)
	v_mfma_f32_32x32x16_bf16 v[64:79], v[232:235], v[80:83], v[0:15]
	ds_read_b128 v[232:235], v252 offset:6752
	s_waitcnt lgkmcnt(5)
	v_mfma_f32_32x32x16_bf16 v[48:63], v[236:239], v[88:91], v[48:63]
	ds_read_b128 v[236:239], v252 offset:128
	s_waitcnt lgkmcnt(5)
	v_mfma_f32_32x32x16_bf16 v[64:79], v[240:243], v[88:91], v[64:79]
	ds_read_b128 v[240:243], v252 offset:6784
	s_waitcnt lgkmcnt(5)
	v_mfma_f32_32x32x16_bf16 v[48:63], v[244:247], v[92:95], v[48:63]
	ds_read_b128 v[244:247], v252 offset:160
	s_waitcnt lgkmcnt(5)
	v_mfma_f32_32x32x16_bf16 v[64:79], v[248:251], v[92:95], v[64:79]
	ds_read_b128 v[248:251], v252 offset:6816
	s_waitcnt lgkmcnt(5)
	v_mfma_f32_32x32x16_bf16 v[48:63], v[176:179], v[96:99], v[48:63]
	ds_read_b128 v[176:179], v252 offset:13312
	s_waitcnt lgkmcnt(5)
	v_mfma_f32_32x32x16_bf16 v[64:79], v[232:235], v[96:99], v[64:79]
	ds_read_b128 v[232:235], v252 offset:19968
	s_waitcnt lgkmcnt(5)
	v_mfma_f32_32x32x16_bf16 v[48:63], v[236:239], v[100:103], v[48:63]
	ds_read_b128 v[236:239], v252 offset:13344
	s_waitcnt lgkmcnt(5)
	v_mfma_f32_32x32x16_bf16 v[64:79], v[240:243], v[100:103], v[64:79]
	ds_read_b128 v[240:243], v252 offset:20000
	s_waitcnt lgkmcnt(5)
	v_mfma_f32_32x32x16_bf16 v[48:63], v[244:247], v[112:115], v[48:63]
	ds_read_b128 v[244:247], v252 offset:13376
	s_waitcnt lgkmcnt(5)
	v_mfma_f32_32x32x16_bf16 v[64:79], v[248:251], v[112:115], v[64:79]
	ds_read_b128 v[248:251], v252 offset:20032
	s_waitcnt lgkmcnt(5)
	v_mfma_f32_32x32x16_bf16 v[144:159], v[176:179], v[80:83], v[0:15]
	ds_read_b128 v[176:179], v252 offset:13408
	s_waitcnt lgkmcnt(5)
	v_mfma_f32_32x32x16_bf16 v[160:175], v[232:235], v[80:83], v[0:15]
	ds_read_b128 v[232:235], v252 offset:20064
	s_nop 4
	v_exp_f32_e32 v48, v48
	v_exp_f32_e32 v49, v49
	v_exp_f32_e32 v50, v50
	s_waitcnt lgkmcnt(5)
	v_mfma_f32_32x32x16_bf16 v[144:159], v[236:239], v[88:91], v[144:159]
	ds_read_b128 v[236:239], v252 offset:13440
	v_exp_f32_e32 v51, v51
	v_exp_f32_e32 v52, v52
	v_exp_f32_e32 v53, v53
	s_waitcnt lgkmcnt(5)
	v_mfma_f32_32x32x16_bf16 v[160:175], v[240:243], v[88:91], v[160:175]
	ds_read_b128 v[240:243], v252 offset:20096
	v_exp_f32_e32 v54, v54
	v_exp_f32_e32 v55, v55
	v_exp_f32_e32 v56, v56
	s_waitcnt lgkmcnt(5)
	v_mfma_f32_32x32x16_bf16 v[144:159], v[244:247], v[92:95], v[144:159]
	ds_read_b128 v[244:247], v252 offset:13472
	v_exp_f32_e32 v57, v57
	v_exp_f32_e32 v58, v58
	v_exp_f32_e32 v59, v59
	s_waitcnt lgkmcnt(5)
	v_mfma_f32_32x32x16_bf16 v[160:175], v[248:251], v[92:95], v[160:175]
	ds_read_b128 v[248:251], v252 offset:20128
	v_exp_f32_e32 v60, v60
	v_exp_f32_e32 v61, v61
	v_exp_f32_e32 v62, v62
	s_waitcnt lgkmcnt(5)
	v_mfma_f32_32x32x16_bf16 v[144:159], v[176:179], v[96:99], v[144:159]
	ds_read_b64_tr_b16 v[176:177], v204 offset:53248
	ds_read_b64_tr_b16 v[178:179], v204 offset:54400
	v_exp_f32_e32 v63, v63
	v_exp_f32_e32 v64, v64
	v_exp_f32_e32 v65, v65
	s_waitcnt lgkmcnt(6)
	v_mfma_f32_32x32x16_bf16 v[160:175], v[232:235], v[96:99], v[160:175]
	ds_read_b64_tr_b16 v[232:233], v204 offset:53312
	ds_read_b64_tr_b16 v[234:235], v204 offset:54464
	v_exp_f32_e32 v66, v66
	v_exp_f32_e32 v67, v67
	v_exp_f32_e32 v68, v68
	s_waitcnt lgkmcnt(7)
	v_mfma_f32_32x32x16_bf16 v[144:159], v[236:239], v[100:103], v[144:159]
	ds_read_b64_tr_b16 v[236:237], v204 offset:55552
	ds_read_b64_tr_b16 v[238:239], v204 offset:56704
	v_exp_f32_e32 v69, v69
	v_exp_f32_e32 v70, v70
	v_exp_f32_e32 v71, v71
	s_waitcnt lgkmcnt(8)
	v_mfma_f32_32x32x16_bf16 v[160:175], v[240:243], v[100:103], v[160:175]
	ds_read_b64_tr_b16 v[240:241], v204 offset:55616
	ds_read_b64_tr_b16 v[242:243], v204 offset:56768
	v_exp_f32_e32 v72, v72
	v_exp_f32_e32 v73, v73
	v_exp_f32_e32 v74, v74
	s_waitcnt lgkmcnt(9)
	v_mfma_f32_32x32x16_bf16 v[144:159], v[244:247], v[112:115], v[144:159]
	v_cvt_pk_bf16_f32 v244, v48, v49
	v_cvt_pk_bf16_f32 v245, v50, v51
	v_cvt_pk_bf16_f32 v246, v52, v53
	v_cvt_pk_bf16_f32 v247, v54, v55
	v_exp_f32_e32 v75, v75
	s_waitcnt lgkmcnt(8)
	v_mfma_f32_32x32x16_bf16 v[160:175], v[248:251], v[112:115], v[160:175]
	v_exp_f32_e32 v76, v76
	v_exp_f32_e32 v77, v77
	v_exp_f32_e32 v78, v78
	s_waitcnt lgkmcnt(6)
	v_mfma_f32_32x32x16_bf16 v[16:31], v[244:247], v[176:179], v[16:31]
	ds_read_b64_tr_b16 v[176:177], v204 offset:57856
	ds_read_b64_tr_b16 v[178:179], v204 offset:59008
	v_cvt_pk_bf16_f32 v248, v56, v57
	v_cvt_pk_bf16_f32 v249, v58, v59
	v_cvt_pk_bf16_f32 v250, v60, v61
	v_cvt_pk_bf16_f32 v251, v62, v63
	v_exp_f32_e32 v79, v79
	v_exp_f32_e32 v144, v144
	s_waitcnt lgkmcnt(6)
	v_mfma_f32_32x32x16_bf16 v[32:47], v[244:247], v[232:235], v[32:47]
	ds_read_b64_tr_b16 v[232:233], v204 offset:57920
	ds_read_b64_tr_b16 v[234:235], v204 offset:59072
	v_cvt_pk_bf16_f32 v244, v64, v65
	v_cvt_pk_bf16_f32 v245, v66, v67
	v_cvt_pk_bf16_f32 v246, v68, v69
	v_cvt_pk_bf16_f32 v247, v70, v71
	v_exp_f32_e32 v145, v145
	v_exp_f32_e32 v146, v146
	s_waitcnt lgkmcnt(6)
	v_mfma_f32_32x32x16_bf16 v[16:31], v[248:251], v[236:239], v[16:31]
	ds_read_b64_tr_b16 v[236:237], v204 offset:60160
	ds_read_b64_tr_b16 v[238:239], v204 offset:61312
	v_exp_f32_e32 v147, v147
	v_exp_f32_e32 v148, v148
	v_exp_f32_e32 v149, v149
	v_exp_f32_e32 v150, v150
	s_waitcnt lgkmcnt(6)
	v_mfma_f32_32x32x16_bf16 v[32:47], v[248:251], v[240:243], v[32:47]
	ds_read_b64_tr_b16 v[240:241], v204 offset:60224
	ds_read_b64_tr_b16 v[242:243], v204 offset:61376
	v_cvt_pk_bf16_f32 v248, v72, v73
	v_cvt_pk_bf16_f32 v249, v74, v75
	v_cvt_pk_bf16_f32 v250, v76, v77
	v_cvt_pk_bf16_f32 v251, v78, v79
	v_exp_f32_e32 v151, v151
	v_exp_f32_e32 v152, v152
	s_waitcnt lgkmcnt(6)
	v_mfma_f32_32x32x16_bf16 v[16:31], v[244:247], v[176:179], v[16:31]
	ds_read_b64_tr_b16 v[176:177], v253 offset:53248
	ds_read_b64_tr_b16 v[178:179], v253 offset:54400
	v_exp_f32_e32 v153, v153
	v_exp_f32_e32 v154, v154
	v_exp_f32_e32 v155, v155
	v_exp_f32_e32 v156, v156
	s_waitcnt lgkmcnt(6)
	v_mfma_f32_32x32x16_bf16 v[32:47], v[244:247], v[232:235], v[32:47]
	ds_read_b64_tr_b16 v[232:233], v253 offset:53312
	ds_read_b64_tr_b16 v[234:235], v253 offset:54464
	v_cvt_pk_bf16_f32 v244, v144, v145
	v_cvt_pk_bf16_f32 v245, v146, v147
	v_cvt_pk_bf16_f32 v246, v148, v149
	v_cvt_pk_bf16_f32 v247, v150, v151
	v_exp_f32_e32 v157, v157
	v_exp_f32_e32 v158, v158
	s_waitcnt lgkmcnt(6)
	v_mfma_f32_32x32x16_bf16 v[16:31], v[248:251], v[236:239], v[16:31]
	ds_read_b64_tr_b16 v[236:237], v253 offset:55552
	ds_read_b64_tr_b16 v[238:239], v253 offset:56704
	v_exp_f32_e32 v159, v159
	v_exp_f32_e32 v160, v160
	v_exp_f32_e32 v161, v161
	v_exp_f32_e32 v162, v162
	s_waitcnt lgkmcnt(6)
	v_mfma_f32_32x32x16_bf16 v[32:47], v[248:251], v[240:243], v[32:47]
	ds_read_b64_tr_b16 v[240:241], v253 offset:55616
	ds_read_b64_tr_b16 v[242:243], v253 offset:56768
	v_cvt_pk_bf16_f32 v248, v152, v153
	v_cvt_pk_bf16_f32 v249, v154, v155
	v_cvt_pk_bf16_f32 v250, v156, v157
	v_cvt_pk_bf16_f32 v251, v158, v159
	v_exp_f32_e32 v163, v163
	v_exp_f32_e32 v164, v164
	s_waitcnt lgkmcnt(6)
	v_mfma_f32_32x32x16_bf16 v[16:31], v[244:247], v[176:179], v[16:31]
	ds_read_b64_tr_b16 v[176:177], v253 offset:57856
	ds_read_b64_tr_b16 v[178:179], v253 offset:59008
	v_exp_f32_e32 v165, v165
	v_exp_f32_e32 v166, v166
	v_exp_f32_e32 v167, v167
	v_exp_f32_e32 v168, v168
	s_waitcnt lgkmcnt(6)
	v_mfma_f32_32x32x16_bf16 v[32:47], v[244:247], v[232:235], v[32:47]
	ds_read_b64_tr_b16 v[232:233], v253 offset:57920
	ds_read_b64_tr_b16 v[234:235], v253 offset:59072
	v_cvt_pk_bf16_f32 v244, v160, v161
	v_cvt_pk_bf16_f32 v245, v162, v163
	v_cvt_pk_bf16_f32 v246, v164, v165
	v_cvt_pk_bf16_f32 v247, v166, v167
	v_exp_f32_e32 v169, v169
	v_exp_f32_e32 v170, v170
	s_waitcnt lgkmcnt(6)
	v_mfma_f32_32x32x16_bf16 v[16:31], v[248:251], v[236:239], v[16:31]
	ds_read_b64_tr_b16 v[236:237], v253 offset:60160
	ds_read_b64_tr_b16 v[238:239], v253 offset:61312
	v_exp_f32_e32 v171, v171
	v_exp_f32_e32 v172, v172
	v_exp_f32_e32 v173, v173
	v_exp_f32_e32 v174, v174
	s_waitcnt lgkmcnt(6)
	v_mfma_f32_32x32x16_bf16 v[32:47], v[248:251], v[240:243], v[32:47]
	ds_read_b64_tr_b16 v[240:241], v253 offset:60224
	ds_read_b64_tr_b16 v[242:243], v253 offset:61376
	v_exp_f32_e32 v175, v175
	v_cvt_pk_bf16_f32 v248, v168, v169
	v_cvt_pk_bf16_f32 v249, v170, v171
	v_cvt_pk_bf16_f32 v250, v172, v173
	v_cvt_pk_bf16_f32 v251, v174, v175
	v_add_f32_e32 v252, v48, v64
	v_add_f32_e32 v252, v252, v49
	s_waitcnt lgkmcnt(6)
	v_mfma_f32_32x32x16_bf16 v[16:31], v[244:247], v[176:179], v[16:31]
	v_add_f32_e32 v252, v252, v65
	v_add_f32_e32 v252, v252, v50
	v_add_f32_e32 v252, v252, v66
	v_add_f32_e32 v252, v252, v51
	v_add_f32_e32 v252, v252, v67
	v_add_f32_e32 v252, v252, v52
	v_add_f32_e32 v252, v252, v68
	v_add_f32_e32 v252, v252, v53
	s_waitcnt lgkmcnt(4)
	v_mfma_f32_32x32x16_bf16 v[32:47], v[244:247], v[232:235], v[32:47]
	v_add_f32_e32 v252, v252, v69
	v_add_f32_e32 v252, v252, v54
	v_add_f32_e32 v252, v252, v70
	v_add_f32_e32 v252, v252, v55
	v_add_f32_e32 v252, v252, v71
	v_add_f32_e32 v252, v252, v56
	v_add_f32_e32 v252, v252, v72
	v_add_f32_e32 v252, v252, v57
	s_waitcnt lgkmcnt(2)
	v_mfma_f32_32x32x16_bf16 v[16:31], v[248:251], v[236:239], v[16:31]
	v_add_f32_e32 v252, v252, v73
	v_add_f32_e32 v252, v252, v58
	v_add_f32_e32 v252, v252, v74
	v_add_f32_e32 v252, v252, v59
	v_add_f32_e32 v252, v252, v75
	v_add_f32_e32 v252, v252, v60
	v_add_f32_e32 v252, v252, v76
	v_add_f32_e32 v252, v252, v61
	s_waitcnt lgkmcnt(0)
	v_mfma_f32_32x32x16_bf16 v[32:47], v[248:251], v[240:243], v[32:47]
	v_add_f32_e32 v252, v252, v77
	v_add_f32_e32 v252, v252, v62
	v_add_f32_e32 v252, v252, v78
	v_add_f32_e32 v252, v252, v63
	v_add_f32_e32 v252, v252, v79
	v_add_f32_e32 v252, v252, v144
	v_add_f32_e32 v252, v252, v160
	v_add_f32_e32 v252, v252, v145
	v_add_f32_e32 v252, v252, v161
	v_add_f32_e32 v252, v252, v146
	v_add_f32_e32 v252, v252, v162
	v_add_f32_e32 v252, v252, v147
	v_add_f32_e32 v252, v252, v163
	v_add_f32_e32 v252, v252, v148
	v_add_f32_e32 v252, v252, v164
	v_add_f32_e32 v252, v252, v149
	v_add_f32_e32 v252, v252, v165
	v_add_f32_e32 v252, v252, v150
	v_add_f32_e32 v252, v252, v166
	v_add_f32_e32 v252, v252, v151
	v_add_f32_e32 v252, v252, v167
	v_add_f32_e32 v252, v252, v152
	v_add_f32_e32 v252, v252, v168
	v_add_f32_e32 v252, v252, v153
	v_add_f32_e32 v252, v252, v169
	v_add_f32_e32 v252, v252, v154
	v_add_f32_e32 v252, v252, v170
	v_add_f32_e32 v252, v252, v155
	v_add_f32_e32 v252, v252, v171
	v_add_f32_e32 v252, v252, v156
	v_add_f32_e32 v252, v252, v172
	v_add_f32_e32 v252, v252, v157
	v_add_f32_e32 v252, v252, v173
	v_add_f32_e32 v252, v252, v158
	v_add_f32_e32 v252, v252, v174
	v_add_f32_e32 v252, v252, v159
	v_add_f32_e32 v252, v252, v175
	v_add_f32_e32 v229, v229, v252
	s_movk_i32 s39, 0x6800
	v_add3_u32 v48, s39, v125, v190
	v_add3_u32 v49, s39, v191, v192
	v_add3_u32 v50, s39, v193, v200
	s_movk_i32 s39, 0x4800
	v_add3_u32 v51, s39, v205, v201
	v_add3_u32 v52, s39, v205, v202
	s_waitcnt vmcnt(5)
	ds_write_b128 v48, v[212:215]
	ds_write_b128 v49, v[216:219]
	ds_write_b128 v50, v[220:223]
	ds_write_b128 v51, v[224:227] offset:53248
	ds_write_b128 v52, v[184:187] offset:53248
	s_waitcnt lgkmcnt(0)
	s_barrier
	s_add_i32 s39, s0, 4
	s_cmp_lt_u32 s39, s23
	s_cbranch_scc0 .Lmy_pa2_nold
	s_add_i32 s39, s0, 3
	s_mul_i32 s40, s39, 0x30000
	s_lshl_b32 s42, s39, 17
	s_add_u32 s40, s16, s40
	s_addc_u32 s41, s17, 0
	s_add_u32 s42, s18, s42
	s_addc_u32 s43, s19, 0
	v_lshl_add_u64 v[48:49], v[132:133], 1, s[40:41]
	v_lshl_add_u64 v[50:51], v[134:135], 1, s[40:41]
	v_lshl_add_u64 v[52:53], v[136:137], 1, s[40:41]
	v_lshl_add_u64 v[54:55], v[138:139], 1, s[42:43]
	v_lshl_add_u64 v[56:57], v[140:141], 1, s[42:43]
	global_load_dwordx4 v[212:215], v[48:49], off
	global_load_dwordx4 v[216:219], v[50:51], off
	global_load_dwordx4 v[220:223], v[52:53], off
	global_load_dwordx4 v[224:227], v[54:55], off
	global_load_dwordx4 v[184:187], v[56:57], off
.Lmy_pa2_nold:
	v_mad_u32_u24 v252, v124, s28, v230
	v_add_u32_e32 v253, 0x2400, v231
	ds_read_b128 v[176:179], v252
	ds_read_b128 v[232:235], v252 offset:6656
	ds_read_b128 v[236:239], v252 offset:32
	ds_read_b128 v[240:243], v252 offset:6688
	ds_read_b128 v[244:247], v252 offset:64
	ds_read_b128 v[248:251], v252 offset:6720
	s_waitcnt lgkmcnt(5)
	v_mfma_f32_32x32x16_bf16 v[48:63], v[176:179], v[80:83], v[0:15]
	ds_read_b128 v[176:179], v252 offset:96
	s_waitcnt lgkmcnt(5)
	v_mfma_f32_32x32x16_bf16 v[64:79], v[232:235], v[80:83], v[0:15]
	ds_read_b128 v[232:235], v252 offset:6752
	s_waitcnt lgkmcnt(5)
	v_mfma_f32_32x32x16_bf16 v[48:63], v[236:239], v[88:91], v[48:63]
	ds_read_b128 v[236:239], v252 offset:128
	s_waitcnt lgkmcnt(5)
	v_mfma_f32_32x32x16_bf16 v[64:79], v[240:243], v[88:91], v[64:79]
	ds_read_b128 v[240:243], v252 offset:6784
	s_waitcnt lgkmcnt(5)
	v_mfma_f32_32x32x16_bf16 v[48:63], v[244:247], v[92:95], v[48:63]
	ds_read_b128 v[244:247], v252 offset:160
	s_waitcnt lgkmcnt(5)
	v_mfma_f32_32x32x16_bf16 v[64:79], v[248:251], v[92:95], v[64:79]
	ds_read_b128 v[248:251], v252 offset:6816
	s_waitcnt lgkmcnt(5)
	v_mfma_f32_32x32x16_bf16 v[48:63], v[176:179], v[96:99], v[48:63]
	ds_read_b128 v[176:179], v252 offset:13312
	s_waitcnt lgkmcnt(5)
	v_mfma_f32_32x32x16_bf16 v[64:79], v[232:235], v[96:99], v[64:79]
	ds_read_b128 v[232:235], v252 offset:19968
	s_waitcnt lgkmcnt(5)
	v_mfma_f32_32x32x16_bf16 v[48:63], v[236:239], v[100:103], v[48:63]
	ds_read_b128 v[236:239], v252 offset:13344
	s_waitcnt lgkmcnt(5)
	v_mfma_f32_32x32x16_bf16 v[64:79], v[240:243], v[100:103], v[64:79]
	ds_read_b128 v[240:243], v252 offset:20000
	s_waitcnt lgkmcnt(5)
	v_mfma_f32_32x32x16_bf16 v[48:63], v[244:247], v[112:115], v[48:63]
	ds_read_b128 v[244:247], v252 offset:13376
	s_waitcnt lgkmcnt(5)
	v_mfma_f32_32x32x16_bf16 v[64:79], v[248:251], v[112:115], v[64:79]
	ds_read_b128 v[248:251], v252 offset:20032
	s_waitcnt lgkmcnt(5)
	v_mfma_f32_32x32x16_bf16 v[144:159], v[176:179], v[80:83], v[0:15]
	ds_read_b128 v[176:179], v252 offset:13408
	s_waitcnt lgkmcnt(5)
	v_mfma_f32_32x32x16_bf16 v[160:175], v[232:235], v[80:83], v[0:15]
	ds_read_b128 v[232:235], v252 offset:20064
	s_nop 4
	v_exp_f32_e32 v48, v48
	v_exp_f32_e32 v49, v49
	v_exp_f32_e32 v50, v50
	s_waitcnt lgkmcnt(5)
	v_mfma_f32_32x32x16_bf16 v[144:159], v[236:239], v[88:91], v[144:159]
	ds_read_b128 v[236:239], v252 offset:13440
	v_exp_f32_e32 v51, v51
	v_exp_f32_e32 v52, v52
	v_exp_f32_e32 v53, v53
	s_waitcnt lgkmcnt(5)
	v_mfma_f32_32x32x16_bf16 v[160:175], v[240:243], v[88:91], v[160:175]
	ds_read_b128 v[240:243], v252 offset:20096
	v_exp_f32_e32 v54, v54
	v_exp_f32_e32 v55, v55
	v_exp_f32_e32 v56, v56
	s_waitcnt lgkmcnt(5)
	v_mfma_f32_32x32x16_bf16 v[144:159], v[244:247], v[92:95], v[144:159]
	ds_read_b128 v[244:247], v252 offset:13472
	v_exp_f32_e32 v57, v57
	v_exp_f32_e32 v58, v58
	v_exp_f32_e32 v59, v59
	s_waitcnt lgkmcnt(5)
	v_mfma_f32_32x32x16_bf16 v[160:175], v[248:251], v[92:95], v[160:175]
	ds_read_b128 v[248:251], v252 offset:20128
	v_exp_f32_e32 v60, v60
	v_exp_f32_e32 v61, v61
	v_exp_f32_e32 v62, v62
	s_waitcnt lgkmcnt(5)
	v_mfma_f32_32x32x16_bf16 v[144:159], v[176:179], v[96:99], v[144:159]
	ds_read_b64_tr_b16 v[176:177], v231 offset:53248
	ds_read_b64_tr_b16 v[178:179], v231 offset:54400
	v_exp_f32_e32 v63, v63
	v_exp_f32_e32 v64, v64
	v_exp_f32_e32 v65, v65
	s_waitcnt lgkmcnt(6)
	v_mfma_f32_32x32x16_bf16 v[160:175], v[232:235], v[96:99], v[160:175]
	ds_read_b64_tr_b16 v[232:233], v231 offset:53312
	ds_read_b64_tr_b16 v[234:235], v231 offset:54464
	v_exp_f32_e32 v66, v66
	v_exp_f32_e32 v67, v67
	v_exp_f32_e32 v68, v68
	s_waitcnt lgkmcnt(7)
	v_mfma_f32_32x32x16_bf16 v[144:159], v[236:239], v[100:103], v[144:159]
	ds_read_b64_tr_b16 v[236:237], v231 offset:55552
	ds_read_b64_tr_b16 v[238:239], v231 offset:56704
	v_exp_f32_e32 v69, v69
	v_exp_f32_e32 v70, v70
	v_exp_f32_e32 v71, v71
	s_waitcnt lgkmcnt(8)
	v_mfma_f32_32x32x16_bf16 v[160:175], v[240:243], v[100:103], v[160:175]
	ds_read_b64_tr_b16 v[240:241], v231 offset:55616
	ds_read_b64_tr_b16 v[242:243], v231 offset:56768
	v_exp_f32_e32 v72, v72
	v_exp_f32_e32 v73, v73
	v_exp_f32_e32 v74, v74
	s_waitcnt lgkmcnt(9)
	v_mfma_f32_32x32x16_bf16 v[144:159], v[244:247], v[112:115], v[144:159]
	v_cvt_pk_bf16_f32 v244, v48, v49
	v_cvt_pk_bf16_f32 v245, v50, v51
	v_cvt_pk_bf16_f32 v246, v52, v53
	v_cvt_pk_bf16_f32 v247, v54, v55
	v_exp_f32_e32 v75, v75
	s_waitcnt lgkmcnt(8)
	v_mfma_f32_32x32x16_bf16 v[160:175], v[248:251], v[112:115], v[160:175]
	v_exp_f32_e32 v76, v76
	v_exp_f32_e32 v77, v77
	v_exp_f32_e32 v78, v78
	s_waitcnt lgkmcnt(6)
	v_mfma_f32_32x32x16_bf16 v[16:31], v[244:247], v[176:179], v[16:31]
	ds_read_b64_tr_b16 v[176:177], v231 offset:57856
	ds_read_b64_tr_b16 v[178:179], v231 offset:59008
	v_cvt_pk_bf16_f32 v248, v56, v57
	v_cvt_pk_bf16_f32 v249, v58, v59
	v_cvt_pk_bf16_f32 v250, v60, v61
	v_cvt_pk_bf16_f32 v251, v62, v63
	v_exp_f32_e32 v79, v79
	v_exp_f32_e32 v144, v144
	s_waitcnt lgkmcnt(6)
	v_mfma_f32_32x32x16_bf16 v[32:47], v[244:247], v[232:235], v[32:47]
	ds_read_b64_tr_b16 v[232:233], v231 offset:57920
	ds_read_b64_tr_b16 v[234:235], v231 offset:59072
	v_cvt_pk_bf16_f32 v244, v64, v65
	v_cvt_pk_bf16_f32 v245, v66, v67
	v_cvt_pk_bf16_f32 v246, v68, v69
	v_cvt_pk_bf16_f32 v247, v70, v71
	v_exp_f32_e32 v145, v145
	v_exp_f32_e32 v146, v146
	s_waitcnt lgkmcnt(6)
	v_mfma_f32_32x32x16_bf16 v[16:31], v[248:251], v[236:239], v[16:31]
	ds_read_b64_tr_b16 v[236:237], v231 offset:60160
	ds_read_b64_tr_b16 v[238:239], v231 offset:61312
	v_exp_f32_e32 v147, v147
	v_exp_f32_e32 v148, v148
	v_exp_f32_e32 v149, v149
	v_exp_f32_e32 v150, v150
	s_waitcnt lgkmcnt(6)
	v_mfma_f32_32x32x16_bf16 v[32:47], v[248:251], v[240:243], v[32:47]
	ds_read_b64_tr_b16 v[240:241], v231 offset:60224
	ds_read_b64_tr_b16 v[242:243], v231 offset:61376
	v_cvt_pk_bf16_f32 v248, v72, v73
	v_cvt_pk_bf16_f32 v249, v74, v75
	v_cvt_pk_bf16_f32 v250, v76, v77
	v_cvt_pk_bf16_f32 v251, v78, v79
	v_exp_f32_e32 v151, v151
	v_exp_f32_e32 v152, v152
	s_waitcnt lgkmcnt(6)
	v_mfma_f32_32x32x16_bf16 v[16:31], v[244:247], v[176:179], v[16:31]
	ds_read_b64_tr_b16 v[176:177], v253 offset:53248
	ds_read_b64_tr_b16 v[178:179], v253 offset:54400
	v_exp_f32_e32 v153, v153
	v_exp_f32_e32 v154, v154
	v_exp_f32_e32 v155, v155
	v_exp_f32_e32 v156, v156
	s_waitcnt lgkmcnt(6)
	v_mfma_f32_32x32x16_bf16 v[32:47], v[244:247], v[232:235], v[32:47]
	ds_read_b64_tr_b16 v[232:233], v253 offset:53312
	ds_read_b64_tr_b16 v[234:235], v253 offset:54464
	v_cvt_pk_bf16_f32 v244, v144, v145
	v_cvt_pk_bf16_f32 v245, v146, v147
	v_cvt_pk_bf16_f32 v246, v148, v149
	v_cvt_pk_bf16_f32 v247, v150, v151
	v_exp_f32_e32 v157, v157
	v_exp_f32_e32 v158, v158
	s_waitcnt lgkmcnt(6)
	v_mfma_f32_32x32x16_bf16 v[16:31], v[248:251], v[236:239], v[16:31]
	ds_read_b64_tr_b16 v[236:237], v253 offset:55552
	ds_read_b64_tr_b16 v[238:239], v253 offset:56704
	v_exp_f32_e32 v159, v159
	v_exp_f32_e32 v160, v160
	v_exp_f32_e32 v161, v161
	v_exp_f32_e32 v162, v162
	s_waitcnt lgkmcnt(6)
	v_mfma_f32_32x32x16_bf16 v[32:47], v[248:251], v[240:243], v[32:47]
	ds_read_b64_tr_b16 v[240:241], v253 offset:55616
	ds_read_b64_tr_b16 v[242:243], v253 offset:56768
	v_cvt_pk_bf16_f32 v248, v152, v153
	v_cvt_pk_bf16_f32 v249, v154, v155
	v_cvt_pk_bf16_f32 v250, v156, v157
	v_cvt_pk_bf16_f32 v251, v158, v159
	v_exp_f32_e32 v163, v163
	v_exp_f32_e32 v164, v164
	s_waitcnt lgkmcnt(6)
	v_mfma_f32_32x32x16_bf16 v[16:31], v[244:247], v[176:179], v[16:31]
	ds_read_b64_tr_b16 v[176:177], v253 offset:57856
	ds_read_b64_tr_b16 v[178:179], v253 offset:59008
	v_exp_f32_e32 v165, v165
	v_exp_f32_e32 v166, v166
	v_exp_f32_e32 v167, v167
	v_exp_f32_e32 v168, v168
	s_waitcnt lgkmcnt(6)
	v_mfma_f32_32x32x16_bf16 v[32:47], v[244:247], v[232:235], v[32:47]
	ds_read_b64_tr_b16 v[232:233], v253 offset:57920
	ds_read_b64_tr_b16 v[234:235], v253 offset:59072
	v_cvt_pk_bf16_f32 v244, v160, v161
	v_cvt_pk_bf16_f32 v245, v162, v163
	v_cvt_pk_bf16_f32 v246, v164, v165
	v_cvt_pk_bf16_f32 v247, v166, v167
	v_exp_f32_e32 v169, v169
	v_exp_f32_e32 v170, v170
	s_waitcnt lgkmcnt(6)
	v_mfma_f32_32x32x16_bf16 v[16:31], v[248:251], v[236:239], v[16:31]
	ds_read_b64_tr_b16 v[236:237], v253 offset:60160
	ds_read_b64_tr_b16 v[238:239], v253 offset:61312
	v_exp_f32_e32 v171, v171
	v_exp_f32_e32 v172, v172
	v_exp_f32_e32 v173, v173
	v_exp_f32_e32 v174, v174
	s_waitcnt lgkmcnt(6)
	v_mfma_f32_32x32x16_bf16 v[32:47], v[248:251], v[240:243], v[32:47]
	ds_read_b64_tr_b16 v[240:241], v253 offset:60224
	ds_read_b64_tr_b16 v[242:243], v253 offset:61376
	v_exp_f32_e32 v175, v175
	v_cvt_pk_bf16_f32 v248, v168, v169
	v_cvt_pk_bf16_f32 v249, v170, v171
	v_cvt_pk_bf16_f32 v250, v172, v173
	v_cvt_pk_bf16_f32 v251, v174, v175
	v_add_f32_e32 v252, v48, v64
	v_add_f32_e32 v252, v252, v49
	s_waitcnt lgkmcnt(6)
	v_mfma_f32_32x32x16_bf16 v[16:31], v[244:247], v[176:179], v[16:31]
	v_add_f32_e32 v252, v252, v65
	v_add_f32_e32 v252, v252, v50
	v_add_f32_e32 v252, v252, v66
	v_add_f32_e32 v252, v252, v51
	v_add_f32_e32 v252, v252, v67
	v_add_f32_e32 v252, v252, v52
	v_add_f32_e32 v252, v252, v68
	v_add_f32_e32 v252, v252, v53
	s_waitcnt lgkmcnt(4)
	v_mfma_f32_32x32x16_bf16 v[32:47], v[244:247], v[232:235], v[32:47]
	v_add_f32_e32 v252, v252, v69
	v_add_f32_e32 v252, v252, v54
	v_add_f32_e32 v252, v252, v70
	v_add_f32_e32 v252, v252, v55
	v_add_f32_e32 v252, v252, v71
	v_add_f32_e32 v252, v252, v56
	v_add_f32_e32 v252, v252, v72
	v_add_f32_e32 v252, v252, v57
	s_waitcnt lgkmcnt(2)
	v_mfma_f32_32x32x16_bf16 v[16:31], v[248:251], v[236:239], v[16:31]
	v_add_f32_e32 v252, v252, v73
	v_add_f32_e32 v252, v252, v58
	v_add_f32_e32 v252, v252, v74
	v_add_f32_e32 v252, v252, v59
	v_add_f32_e32 v252, v252, v75
	v_add_f32_e32 v252, v252, v60
	v_add_f32_e32 v252, v252, v76
	v_add_f32_e32 v252, v252, v61
	s_waitcnt lgkmcnt(0)
	v_mfma_f32_32x32x16_bf16 v[32:47], v[248:251], v[240:243], v[32:47]
	v_add_f32_e32 v252, v252, v77
	v_add_f32_e32 v252, v252, v62
	v_add_f32_e32 v252, v252, v78
	v_add_f32_e32 v252, v252, v63
	v_add_f32_e32 v252, v252, v79
	v_add_f32_e32 v252, v252, v144
	v_add_f32_e32 v252, v252, v160
	v_add_f32_e32 v252, v252, v145
	v_add_f32_e32 v252, v252, v161
	v_add_f32_e32 v252, v252, v146
	v_add_f32_e32 v252, v252, v162
	v_add_f32_e32 v252, v252, v147
	v_add_f32_e32 v252, v252, v163
	v_add_f32_e32 v252, v252, v148
	v_add_f32_e32 v252, v252, v164
	v_add_f32_e32 v252, v252, v149
	v_add_f32_e32 v252, v252, v165
	v_add_f32_e32 v252, v252, v150
	v_add_f32_e32 v252, v252, v166
	v_add_f32_e32 v252, v252, v151
	v_add_f32_e32 v252, v252, v167
	v_add_f32_e32 v252, v252, v152
	v_add_f32_e32 v252, v252, v168
	v_add_f32_e32 v252, v252, v153
	v_add_f32_e32 v252, v252, v169
	v_add_f32_e32 v252, v252, v154
	v_add_f32_e32 v252, v252, v170
	v_add_f32_e32 v252, v252, v155
	v_add_f32_e32 v252, v252, v171
	v_add_f32_e32 v252, v252, v156
	v_add_f32_e32 v252, v252, v172
	v_add_f32_e32 v252, v252, v157
	v_add_f32_e32 v252, v252, v173
	v_add_f32_e32 v252, v252, v158
	v_add_f32_e32 v252, v252, v174
	v_add_f32_e32 v252, v252, v159
	v_add_f32_e32 v252, v252, v175
	v_add_f32_e32 v229, v229, v252
	s_add_i32 s0, s0, 2
	s_add_i32 s39, s0, 2
	s_cmp_lt_u32 s39, s23
	s_cbranch_scc1 .Lmy_pa2_pair
	v_subrev_u32_e32 v181, 32, v180
	v_subrev_u32_e32 v182, 33, v180
	v_subrev_u32_e32 v183, 34, v180
	v_subrev_u32_e32 v184, 35, v180
	v_add_u32_e32 v185, -8, v180
	v_subrev_u32_e32 v186, 40, v180
	v_add_u32_e32 v187, -9, v180
	v_subrev_u32_e32 v188, 41, v180
	v_add_u32_e32 v189, -10, v180
	v_subrev_u32_e32 v210, 42, v180
	v_add_u32_e32 v211, -11, v180
	v_subrev_u32_e32 v212, 43, v180
	v_add_u32_e32 v213, -16, v180
	v_subrev_u32_e32 v214, 48, v180
	v_subrev_u32_e32 v215, 17, v180
	v_subrev_u32_e32 v216, 49, v180
	v_subrev_u32_e32 v217, 18, v180
	v_subrev_u32_e32 v218, 50, v180
	v_subrev_u32_e32 v219, 19, v180
	v_subrev_u32_e32 v220, 51, v180
	v_subrev_u32_e32 v221, 24, v180
	v_subrev_u32_e32 v222, 56, v180
	v_subrev_u32_e32 v223, 25, v180
	v_subrev_u32_e32 v224, 57, v180
	v_subrev_u32_e32 v225, 26, v180
	v_subrev_u32_e32 v226, 58, v180
	v_subrev_u32_e32 v227, 27, v180
	v_subrev_u32_e32 v228, 59, v180
.Lmy_pa2_skip:
.LBB0_1565:
	s_and_b32 s12, s0, 1
	s_mul_i32 s1, s12, 0x6800
	s_add_i32 s6, s1, 0
	v_add3_u32 v48, s6, v125, v190
	s_waitcnt vmcnt(3)
	ds_write_b128 v48, v[104:107]
	v_add3_u32 v48, s6, v191, v192
	s_waitcnt vmcnt(2)
	ds_write_b128 v48, v[108:111]
	v_add3_u32 v48, s6, v193, v200
	s_mulk_i32 s12, 0x4800
	s_waitcnt vmcnt(1)
	ds_write_b128 v48, v[116:119]
	v_add_u32_e32 v48, s12, v205
	s_add_i32 s6, s0, 1
	v_add_u32_e32 v49, v48, v201
	v_add_u32_e32 v48, v48, v202
	s_cmp_ge_u32 s6, s23
	s_waitcnt vmcnt(0)
	ds_write_b128 v49, v[120:123] offset:53248
	ds_write_b128 v48, v[84:87] offset:53248
	s_waitcnt lgkmcnt(0)
	s_barrier
	s_cbranch_scc1 .LBB0_1567
	s_mul_i32 s39, s6, 0x30000
	s_mul_hi_u32 s13, s6, 0x30000
	s_add_u32 s40, s16, s39
	s_addc_u32 s41, s17, s13
	s_lshl_b64 s[42:43], s[6:7], 17
	v_lshl_add_u64 v[48:49], v[132:133], 1, s[40:41]
	v_lshl_add_u64 v[50:51], v[134:135], 1, s[40:41]
	global_load_dwordx4 v[104:107], v[48:49], off
	global_load_dwordx4 v[108:111], v[50:51], off
	v_lshl_add_u64 v[48:49], v[136:137], 1, s[40:41]
	s_add_u32 s40, s18, s42
	s_addc_u32 s41, s19, s43
	v_lshl_add_u64 v[50:51], v[138:139], 1, s[40:41]
	global_load_dwordx4 v[116:119], v[48:49], off
	global_load_dwordx4 v[120:123], v[50:51], off
	v_lshl_add_u64 v[48:49], v[140:141], 1, s[40:41]
	global_load_dwordx4 v[84:87], v[48:49], off
